# K-loops: no s_setprio, saddr-form LDS-DMA, B-fragment LDS base precomputed, loop heads 64B-aligned
# speedup vs baseline: 1.0197x; 1.0068x over previous
; #define PG8_STAGE(bufoff, gbase, voff) do { _Pragma("unroll") for (int _i = 0; _i < 2; ++_i) \
;         __builtin_amdgcn_global_load_lds((const unsigned*)((const char*)(gbase) + (voff)[_i]), (LAS unsigned*)(lds + (bufoff) + ldsw + _i * 8192), 16, 0, 0); } while (0)
; #define PG8_LDA(dst, b, h) do { _Pragma("unroll") for (int m = 0; m < 4; ++m) _Pragma("unroll") for (int k = 0; k < 2; ++k) dst[m][k] = *(const LAS bf16x8*)(lds + PG8_SA(b, h) + aoff + m * 2048 + k * 1024); } while (0)
; #define PG8_WAIT_V(n) asm volatile("s_waitcnt vmcnt(" #n ")" ::: "memory")
; #define PG8_WAIT_L(n) asm volatile("s_waitcnt lgkmcnt(" #n ")" ::: "memory")
; template <class Prog>
; __device__ __forceinline__ void gemm_phase(LAS unsigned char* lds, const int K, const Prog& S) {
;     ...
;     Unit cur, nxt; int ui = 0;
;     if (!S.next(0, cur)) return;
;     f32x4 acc[2][2][4][2];
; #pragma unroll
;     for (int a = 0; a < 2; ++a)
; #pragma unroll
;         for (int b = 0; b < 2; ++b)
; #pragma unroll
;             for (int m = 0; m < 4; ++m)
; #pragma unroll
;                 for (int n = 0; n < 2; ++n) acc[a][b][m][n] = (f32x4){0.f, 0.f, 0.f, 0.f};
;     bf16x8 At[4][2], B0[2][2], B1[2][2];
;     const char* cA = cur.a; const char* cB = cur.b;
;     PG8_STAGE(PG8_SB(0, 0), cB, voffB); PG8_STAGE(PG8_SA(0, 0), cA, voffA); PG8_STAGE(PG8_SB(0, 1), cB + hstep, voffB); PG8_STAGE(PG8_SA(0, 1), cA + hstep, voffA);
;     if (wr == 1) PG8_BAR;
;     PG8_WAIT_V(4); PG8_BAR;
;     PG8_STAGE(PG8_SB(1, 0), cB + kstep, voffB); PG8_STAGE(PG8_SA(1, 0), cA + kstep, voffA); PG8_STAGE(PG8_SB(1, 1), cB + hstep + kstep, voffB);
;     PG8_WAIT_V(6); PG8_BAR;
;     for (;;) {
;         const bool has_next = S.next(ui + 1, nxt);
;         const char* nA = has_next ? nxt.a : cA; const char* nB = has_next ? nxt.b : cB;
;         for (int t = 0; t < nt; t += 2) {
;             const bool last = (t == nt - 2);
;             const char* a1 = cA + (size_t)(t + 1) * kstep;
;             const char* a2 = last ? nA : cA + (size_t)(t + 2) * kstep; const char* b2 = last ? nB : cB + (size_t)(t + 2) * kstep;
;             const char* a3 = a2 + kstep; const char* b3 = b2 + kstep;
;             PG8_LDB(B0, 0, 0); PG8_SCHED; PG8_LDA(At, 0, 0); PG8_STAGE(PG8_SA(1, 1), a1 + hstep, voffA);
;             PG8_WAIT_L(8); PG8_BAR; PG8_WAIT_L(0); PG8_MMA(0, 0, At, B0); PG8_BAR; PG8_SCHED;
.LBB0_100:
	s_add_u32 s40, s40, 0x80080
	s_addc_u32 s41, s41, 0
	s_add_u32 s9, s44, 0x100
	v_mov_b32_e32 v0, 0
	s_addc_u32 s15, s45, 0
	s_mov_b32 s69, -2
	v_mov_b32_e32 v1, v0
	v_mov_b32_e32 v2, v0
	v_mov_b32_e32 v3, v0
	v_mov_b32_e32 v8, v0
	v_mov_b32_e32 v9, v0
	v_mov_b32_e32 v10, v0
	v_mov_b32_e32 v11, v0
	v_mov_b32_e32 v16, v0
	v_mov_b32_e32 v17, v0
	v_mov_b32_e32 v18, v0
	v_mov_b32_e32 v19, v0
	s_waitcnt vmcnt(16)
	v_mov_b32_e32 v24, v0
	v_mov_b32_e32 v25, v0
	v_mov_b32_e32 v26, v0
	v_mov_b32_e32 v27, v0
	v_mov_b32_e32 v32, v0
	v_mov_b32_e32 v33, v0
	v_mov_b32_e32 v34, v0
	v_mov_b32_e32 v35, v0
	v_mov_b32_e32 v40, v0
	v_mov_b32_e32 v41, v0
	v_mov_b32_e32 v42, v0
	v_mov_b32_e32 v43, v0
	v_mov_b32_e32 v48, v0
	v_mov_b32_e32 v49, v0
	v_mov_b32_e32 v50, v0
	v_mov_b32_e32 v51, v0
	v_mov_b32_e32 v56, v0
	v_mov_b32_e32 v57, v0
	v_mov_b32_e32 v58, v0
	v_mov_b32_e32 v59, v0
	v_mov_b32_e32 v4, v0
	v_mov_b32_e32 v5, v0
	v_mov_b32_e32 v6, v0
	v_mov_b32_e32 v7, v0
	v_mov_b32_e32 v12, v0
	v_mov_b32_e32 v13, v0
	v_mov_b32_e32 v14, v0
	v_mov_b32_e32 v15, v0
	v_mov_b32_e32 v20, v0
	v_mov_b32_e32 v21, v0
	v_mov_b32_e32 v22, v0
	v_mov_b32_e32 v23, v0
	v_mov_b32_e32 v28, v0
	v_mov_b32_e32 v29, v0
	v_mov_b32_e32 v30, v0
	v_mov_b32_e32 v31, v0
	v_mov_b32_e32 v36, v0
	v_mov_b32_e32 v37, v0
	v_mov_b32_e32 v38, v0
	v_mov_b32_e32 v39, v0
	v_mov_b32_e32 v44, v0
	v_mov_b32_e32 v45, v0
	v_mov_b32_e32 v46, v0
	v_mov_b32_e32 v47, v0
	v_mov_b32_e32 v52, v0
	v_mov_b32_e32 v53, v0
	v_mov_b32_e32 v54, v0
	v_mov_b32_e32 v55, v0
	v_mov_b32_e32 v60, v0
	v_mov_b32_e32 v61, v0
	v_mov_b32_e32 v62, v0
	v_mov_b32_e32 v63, v0
	v_mov_b32_e32 v64, v0
	v_mov_b32_e32 v65, v0
	v_mov_b32_e32 v66, v0
	v_mov_b32_e32 v67, v0
	v_mov_b32_e32 v72, v0
	v_mov_b32_e32 v73, v0
	v_mov_b32_e32 v74, v0
	v_mov_b32_e32 v75, v0
	v_mov_b32_e32 v80, v0
	v_mov_b32_e32 v81, v0
	v_mov_b32_e32 v82, v0
	v_mov_b32_e32 v83, v0
	v_mov_b32_e32 v88, v0
	v_mov_b32_e32 v89, v0
	v_mov_b32_e32 v90, v0
	v_mov_b32_e32 v91, v0
	v_mov_b32_e32 v96, v0
	v_mov_b32_e32 v97, v0
	v_mov_b32_e32 v98, v0
	v_mov_b32_e32 v99, v0
	v_mov_b32_e32 v104, v0
	v_mov_b32_e32 v105, v0
	v_mov_b32_e32 v106, v0
	v_mov_b32_e32 v107, v0
	v_mov_b32_e32 v112, v0
	v_mov_b32_e32 v113, v0
	v_mov_b32_e32 v114, v0
	v_mov_b32_e32 v115, v0
	v_mov_b32_e32 v120, v0
	v_mov_b32_e32 v121, v0
	v_mov_b32_e32 v122, v0
	v_mov_b32_e32 v123, v0
	v_mov_b32_e32 v68, v0
	v_mov_b32_e32 v69, v0
	v_mov_b32_e32 v70, v0
	v_mov_b32_e32 v71, v0
	v_mov_b32_e32 v76, v0
	v_mov_b32_e32 v77, v0
	v_mov_b32_e32 v78, v0
	v_mov_b32_e32 v79, v0
	v_mov_b32_e32 v84, v0
	v_mov_b32_e32 v85, v0
	v_mov_b32_e32 v86, v0
	v_mov_b32_e32 v87, v0
	v_mov_b32_e32 v92, v0
	v_mov_b32_e32 v93, v0
	v_mov_b32_e32 v94, v0
	v_mov_b32_e32 v95, v0
	v_mov_b32_e32 v100, v0
	v_mov_b32_e32 v101, v0
	v_mov_b32_e32 v102, v0
	v_mov_b32_e32 v103, v0
	v_mov_b32_e32 v108, v0
	v_mov_b32_e32 v109, v0
	v_mov_b32_e32 v110, v0
	v_mov_b32_e32 v111, v0
	v_mov_b32_e32 v116, v0
	v_mov_b32_e32 v117, v0
	v_mov_b32_e32 v118, v0
	v_mov_b32_e32 v119, v0
	v_mov_b32_e32 v124, v0
	v_mov_b32_e32 v125, v0
	v_mov_b32_e32 v126, v0
	v_mov_b32_e32 v127, v0
	v_add_u32_e32 v244, 0x10000, v205
	.p2align 6
.LBB0_101:
	s_add_u32 s44, s40, 0xfff80080
	s_addc_u32 s45, s41, -1
	s_cmp_eq_u32 s69, 28
	s_cselect_b32 s47, s5, s45
	s_cselect_b32 s46, s4, s44
	s_cselect_b32 s45, s13, s15
	s_cselect_b32 s44, s12, s9
	s_add_u32 s76, s40, 0xfff80000
	s_addc_u32 s77, s41, -1
	ds_read_b128 v[128:131], v244
	ds_read_b128 v[132:135], v244 offset:1024
	ds_read_b128 v[136:139], v244 offset:2048
	ds_read_b128 v[140:143], v244 offset:3072
	s_add_i32 m0, s92, 0x8000
	ds_read_b128 v[188:191], v244 offset:16384
	ds_read_b128 v[196:199], v244 offset:17408
	ds_read_b128 v[200:203], v244 offset:18432
	ds_read_b128 v[218:221], v244 offset:19456
	global_load_lds_dwordx4 v184, s[76:77]
	s_add_i32 m0, s92, 0xa000
	ds_read_b128 v[144:147], v216
	ds_read_b128 v[148:151], v216 offset:1024
	ds_read_b128 v[152:155], v216 offset:2048
	ds_read_b128 v[156:159], v216 offset:3072
	global_load_lds_dwordx4 v186, s[76:77]
	s_add_i32 m0, s92, 0xc000
	ds_read_b128 v[160:163], v216 offset:4096
	ds_read_b128 v[164:167], v216 offset:5120
	ds_read_b128 v[168:171], v216 offset:6144
	ds_read_b128 v[172:175], v216 offset:7168
	global_load_lds_dwordx4 v184, s[40:41]
	s_add_i32 m0, s92, 0xe000
	s_nop 0
	global_load_lds_dwordx4 v186, s[40:41]
	s_waitcnt lgkmcnt(0)
	s_barrier
	v_mfma_f32_16x16x32_bf16 v[124:127], v[128:131], v[144:147], v[124:127]
	v_mfma_f32_16x16x32_bf16 v[116:119], v[136:139], v[144:147], v[116:119]
	v_mfma_f32_16x16x32_bf16 v[108:111], v[128:131], v[152:155], v[108:111]
	v_mfma_f32_16x16x32_bf16 v[100:103], v[136:139], v[152:155], v[100:103]
	v_mfma_f32_16x16x32_bf16 v[92:95], v[128:131], v[160:163], v[92:95]
	v_mfma_f32_16x16x32_bf16 v[84:87], v[136:139], v[160:163], v[84:87]
	v_mfma_f32_16x16x32_bf16 v[76:79], v[128:131], v[168:171], v[76:79]
	v_mfma_f32_16x16x32_bf16 v[68:71], v[136:139], v[168:171], v[68:71]
	v_mfma_f32_16x16x32_bf16 v[124:127], v[132:135], v[148:151], v[124:127]
	v_mfma_f32_16x16x32_bf16 v[116:119], v[140:143], v[148:151], v[116:119]
	v_mfma_f32_16x16x32_bf16 v[108:111], v[132:135], v[156:159], v[108:111]
	v_mfma_f32_16x16x32_bf16 v[100:103], v[140:143], v[156:159], v[100:103]
	v_mfma_f32_16x16x32_bf16 v[92:95], v[132:135], v[164:167], v[92:95]
	v_mfma_f32_16x16x32_bf16 v[84:87], v[140:143], v[164:167], v[84:87]
	v_mfma_f32_16x16x32_bf16 v[76:79], v[132:135], v[172:175], v[76:79]
	v_mfma_f32_16x16x32_bf16 v[68:71], v[140:143], v[172:175], v[68:71]
	v_mfma_f32_16x16x32_bf16 v[120:123], v[188:191], v[144:147], v[120:123]
	v_mfma_f32_16x16x32_bf16 v[112:115], v[200:203], v[144:147], v[112:115]
	v_mfma_f32_16x16x32_bf16 v[104:107], v[188:191], v[152:155], v[104:107]
	v_mfma_f32_16x16x32_bf16 v[96:99], v[200:203], v[152:155], v[96:99]
	v_mfma_f32_16x16x32_bf16 v[88:91], v[188:191], v[160:163], v[88:91]
	v_mfma_f32_16x16x32_bf16 v[80:83], v[200:203], v[160:163], v[80:83]
	v_mfma_f32_16x16x32_bf16 v[72:75], v[188:191], v[168:171], v[72:75]
	v_mfma_f32_16x16x32_bf16 v[64:67], v[200:203], v[168:171], v[64:67]
	v_mfma_f32_16x16x32_bf16 v[120:123], v[196:199], v[148:151], v[120:123]
	v_mfma_f32_16x16x32_bf16 v[112:115], v[218:221], v[148:151], v[112:115]
	v_mfma_f32_16x16x32_bf16 v[104:107], v[196:199], v[156:159], v[104:107]
	v_mfma_f32_16x16x32_bf16 v[96:99], v[218:221], v[156:159], v[96:99]
	v_mfma_f32_16x16x32_bf16 v[88:91], v[196:199], v[164:167], v[88:91]
	v_mfma_f32_16x16x32_bf16 v[80:83], v[218:221], v[164:167], v[80:83]
	v_mfma_f32_16x16x32_bf16 v[72:75], v[196:199], v[172:175], v[72:75]
	v_mfma_f32_16x16x32_bf16 v[64:67], v[218:221], v[172:175], v[64:67]
	s_barrier
; #define PG8_STAGE(bufoff, gbase, voff) do { _Pragma("unroll") for (int _i = 0; _i < 2; ++_i) \
;         __builtin_amdgcn_global_load_lds((const unsigned*)((const char*)(gbase) + (voff)[_i]), (LAS unsigned*)(lds + (bufoff) + ldsw + _i * 8192), 16, 0, 0); } while (0)
; #define PG8_LDA(dst, b, h) do { _Pragma("unroll") for (int m = 0; m < 4; ++m) _Pragma("unroll") for (int k = 0; k < 2; ++k) dst[m][k] = *(const LAS bf16x8*)(lds + PG8_SA(b, h) + aoff + m * 2048 + k * 1024); } while (0)
; #define PG8_LDB(dst, b, h) do { _Pragma("unroll") for (int n = 0; n < 2; ++n) _Pragma("unroll") for (int k = 0; k < 2; ++k) dst[n][k] = *(const LAS bf16x8*)(lds + PG8_SB(b, h) + boff + n * 2048 + k * 1024); } while (0)
; #define PG8_MMA(ai, bj, At, Bt) do { __builtin_amdgcn_s_setprio(1); _Pragma("unroll") for (int m = 0; m < 4; ++m) _Pragma("unroll") for (int n = 0; n < 2; ++n) _Pragma("unroll") for (int k = 0; k < 2; ++k) \
;         acc[ai][bj][m][n] = __builtin_amdgcn_mfma_f32_16x16x32_bf16(Bt[n][k], At[m][k], acc[ai][bj][m][n], 0, 0, 0); __builtin_amdgcn_s_setprio(0); } while (0)
; #define PG8_WAIT_V(n) asm volatile("s_waitcnt vmcnt(" #n ")" ::: "memory")
; #define PG8_WAIT_L(n) asm volatile("s_waitcnt lgkmcnt(" #n ")" ::: "memory")
; #define PG8_BAR __builtin_amdgcn_s_barrier()
; #define PG8_SCHED __builtin_amdgcn_sched_barrier(0)
; template <class Prog>
; __device__ __forceinline__ void gemm_phase(LAS unsigned char* lds, const int K, const Prog& S) {
;     ...
;             PG8_WAIT_L(8); PG8_BAR; PG8_WAIT_L(0); PG8_MMA(0, 0, At, B0); PG8_BAR; PG8_SCHED;
;             PG8_LDB(B1, 0, 1); PG8_STAGE(PG8_SB(0, 0), b2, voffB);
;             PG8_BAR; PG8_WAIT_L(0); PG8_MMA(0, 1, At, B1); PG8_BAR;
;             PG8_LDA(At, 0, 1); PG8_STAGE(PG8_SA(0, 0), a2, voffA);
;             PG8_BAR; PG8_WAIT_L(0); PG8_MMA(1, 0, At, B0); PG8_BAR; PG8_SCHED;
;             PG8_STAGE(PG8_SB(0, 1), b2 + hstep, voffB);
;             PG8_WAIT_V(6); PG8_BAR; PG8_MMA(1, 1, At, B1); PG8_BAR;
;             PG8_LDB(B0, 1, 0); PG8_SCHED; PG8_LDA(At, 1, 0); PG8_STAGE(PG8_SA(0, 1), a2 + hstep, voffA);
	ds_read_b128 v[144:147], v216 offset:16384
	ds_read_b128 v[148:151], v216 offset:17408
	ds_read_b128 v[152:155], v216 offset:18432
	ds_read_b128 v[156:159], v216 offset:19456
	s_add_i32 m0, s92, 0x10000
	ds_read_b128 v[160:163], v216 offset:20480
	ds_read_b128 v[164:167], v216 offset:21504
	ds_read_b128 v[168:171], v216 offset:22528
	ds_read_b128 v[172:175], v216 offset:23552
	global_load_lds_dwordx4 v192, s[44:45]
	s_add_i32 m0, s92, 0x12000
	s_nop 0
	global_load_lds_dwordx4 v180, s[44:45]
	s_add_u32 s76, s44, 0x80000
	s_addc_u32 s77, s45, 0
	s_add_i32 m0, s92, 0x14000
	s_nop 0
	global_load_lds_dwordx4 v192, s[76:77]
	s_add_i32 m0, s92, 0x16000
	s_nop 0
	global_load_lds_dwordx4 v180, s[76:77]
	s_waitcnt vmcnt(4)
	s_waitcnt lgkmcnt(0)
	s_barrier
	v_mfma_f32_16x16x32_bf16 v[60:63], v[128:131], v[144:147], v[60:63]
	v_mfma_f32_16x16x32_bf16 v[52:55], v[136:139], v[144:147], v[52:55]
	v_mfma_f32_16x16x32_bf16 v[44:47], v[128:131], v[152:155], v[44:47]
	v_mfma_f32_16x16x32_bf16 v[36:39], v[136:139], v[152:155], v[36:39]
	v_mfma_f32_16x16x32_bf16 v[28:31], v[128:131], v[160:163], v[28:31]
	v_mfma_f32_16x16x32_bf16 v[20:23], v[136:139], v[160:163], v[20:23]
	v_mfma_f32_16x16x32_bf16 v[12:15], v[128:131], v[168:171], v[12:15]
	v_mfma_f32_16x16x32_bf16 v[4:7], v[136:139], v[168:171], v[4:7]
	v_mfma_f32_16x16x32_bf16 v[60:63], v[132:135], v[148:151], v[60:63]
	v_mfma_f32_16x16x32_bf16 v[52:55], v[140:143], v[148:151], v[52:55]
	v_mfma_f32_16x16x32_bf16 v[44:47], v[132:135], v[156:159], v[44:47]
	v_mfma_f32_16x16x32_bf16 v[36:39], v[140:143], v[156:159], v[36:39]
	v_mfma_f32_16x16x32_bf16 v[28:31], v[132:135], v[164:167], v[28:31]
	v_mfma_f32_16x16x32_bf16 v[20:23], v[140:143], v[164:167], v[20:23]
	v_mfma_f32_16x16x32_bf16 v[12:15], v[132:135], v[172:175], v[12:15]
	v_mfma_f32_16x16x32_bf16 v[4:7], v[140:143], v[172:175], v[4:7]
	v_mfma_f32_16x16x32_bf16 v[56:59], v[188:191], v[144:147], v[56:59]
	v_mfma_f32_16x16x32_bf16 v[48:51], v[200:203], v[144:147], v[48:51]
	v_mfma_f32_16x16x32_bf16 v[40:43], v[188:191], v[152:155], v[40:43]
	v_mfma_f32_16x16x32_bf16 v[32:35], v[200:203], v[152:155], v[32:35]
	v_mfma_f32_16x16x32_bf16 v[24:27], v[188:191], v[160:163], v[24:27]
	v_mfma_f32_16x16x32_bf16 v[16:19], v[200:203], v[160:163], v[16:19]
	v_mfma_f32_16x16x32_bf16 v[8:11], v[188:191], v[168:171], v[8:11]
	v_mfma_f32_16x16x32_bf16 v[0:3], v[200:203], v[168:171], v[0:3]
	v_mfma_f32_16x16x32_bf16 v[56:59], v[196:199], v[148:151], v[56:59]
	v_mfma_f32_16x16x32_bf16 v[48:51], v[218:221], v[148:151], v[48:51]
	v_mfma_f32_16x16x32_bf16 v[40:43], v[196:199], v[156:159], v[40:43]
	v_mfma_f32_16x16x32_bf16 v[32:35], v[218:221], v[156:159], v[32:35]
	v_mfma_f32_16x16x32_bf16 v[24:27], v[196:199], v[164:167], v[24:27]
	v_mfma_f32_16x16x32_bf16 v[16:19], v[218:221], v[164:167], v[16:19]
	v_mfma_f32_16x16x32_bf16 v[8:11], v[196:199], v[172:175], v[8:11]
	v_mfma_f32_16x16x32_bf16 v[0:3], v[218:221], v[172:175], v[0:3]
	s_barrier
	s_add_u32 s76, s46, 0x80000
	s_addc_u32 s77, s47, 0
	ds_read_b128 v[128:131], v244 offset:32768
	ds_read_b128 v[132:135], v244 offset:33792
	ds_read_b128 v[136:139], v244 offset:34816
	ds_read_b128 v[140:143], v244 offset:35840
	s_mov_b32 m0, s92
	ds_read_b128 v[188:191], v244 offset:49152
	ds_read_b128 v[196:199], v244 offset:50176
	ds_read_b128 v[200:203], v244 offset:51200
	ds_read_b128 v[218:221], v244 offset:52224
	global_load_lds_dwordx4 v176, s[46:47]
	s_add_i32 m0, s92, 0x2000
	ds_read_b128 v[144:147], v216 offset:32768
	ds_read_b128 v[148:151], v216 offset:33792
	ds_read_b128 v[152:155], v216 offset:34816
	ds_read_b128 v[156:159], v216 offset:35840
	global_load_lds_dwordx4 v178, s[46:47]
	s_add_i32 m0, s92, 0x4000
	ds_read_b128 v[160:163], v216 offset:36864
	ds_read_b128 v[164:167], v216 offset:37888
	ds_read_b128 v[168:171], v216 offset:38912
	ds_read_b128 v[172:175], v216 offset:39936
	global_load_lds_dwordx4 v176, s[76:77]
	s_add_i32 m0, s92, 0x6000
	s_nop 0
	global_load_lds_dwordx4 v178, s[76:77]
	s_waitcnt lgkmcnt(0)
	s_barrier
; #define PG8_STAGE(bufoff, gbase, voff) do { _Pragma("unroll") for (int _i = 0; _i < 2; ++_i) \
;         __builtin_amdgcn_global_load_lds((const unsigned*)((const char*)(gbase) + (voff)[_i]), (LAS unsigned*)(lds + (bufoff) + ldsw + _i * 8192), 16, 0, 0); } while (0)
; #define PG8_LDA(dst, b, h) do { _Pragma("unroll") for (int m = 0; m < 4; ++m) _Pragma("unroll") for (int k = 0; k < 2; ++k) dst[m][k] = *(const LAS bf16x8*)(lds + PG8_SA(b, h) + aoff + m * 2048 + k * 1024); } while (0)
; #define PG8_LDB(dst, b, h) do { _Pragma("unroll") for (int n = 0; n < 2; ++n) _Pragma("unroll") for (int k = 0; k < 2; ++k) dst[n][k] = *(const LAS bf16x8*)(lds + PG8_SB(b, h) + boff + n * 2048 + k * 1024); } while (0)
; #define PG8_MMA(ai, bj, At, Bt) do { __builtin_amdgcn_s_setprio(1); _Pragma("unroll") for (int m = 0; m < 4; ++m) _Pragma("unroll") for (int n = 0; n < 2; ++n) _Pragma("unroll") for (int k = 0; k < 2; ++k) \
;         acc[ai][bj][m][n] = __builtin_amdgcn_mfma_f32_16x16x32_bf16(Bt[n][k], At[m][k], acc[ai][bj][m][n], 0, 0, 0); __builtin_amdgcn_s_setprio(0); } while (0)
; #define PG8_WAIT_V(n) asm volatile("s_waitcnt vmcnt(" #n ")" ::: "memory")
; #define PG8_WAIT_L(n) asm volatile("s_waitcnt lgkmcnt(" #n ")" ::: "memory")
; #define PG8_BAR __builtin_amdgcn_s_barrier()
; #define PG8_SCHED __builtin_amdgcn_sched_barrier(0)
; template <class Prog>
; __device__ __forceinline__ void gemm_phase(LAS unsigned char* lds, const int K, const Prog& S) {
;     ...
;             PG8_LDB(B0, 1, 0); PG8_SCHED; PG8_LDA(At, 1, 0); PG8_STAGE(PG8_SA(0, 1), a2 + hstep, voffA);
;             PG8_WAIT_L(8); PG8_BAR; PG8_WAIT_L(0); PG8_MMA(0, 0, At, B0); PG8_BAR; PG8_SCHED;
;             PG8_LDB(B1, 1, 1); PG8_STAGE(PG8_SB(1, 0), b3, voffB);
;             PG8_BAR; PG8_WAIT_L(0); PG8_MMA(0, 1, At, B1); PG8_BAR;
;             PG8_LDA(At, 1, 1); PG8_STAGE(PG8_SA(1, 0), a3, voffA);
;             PG8_BAR; PG8_WAIT_L(0); PG8_MMA(1, 0, At, B0); PG8_BAR; PG8_SCHED;
;             PG8_STAGE(PG8_SB(1, 1), b3 + hstep, voffB);
;             PG8_WAIT_V(6); PG8_BAR; PG8_MMA(1, 1, At, B1); PG8_BAR;
;         }
;         S.epi(acc, cur, wr, wc, fr, fq);
	v_mfma_f32_16x16x32_bf16 v[124:127], v[128:131], v[144:147], v[124:127]
	v_mfma_f32_16x16x32_bf16 v[116:119], v[136:139], v[144:147], v[116:119]
	v_mfma_f32_16x16x32_bf16 v[108:111], v[128:131], v[152:155], v[108:111]
	v_mfma_f32_16x16x32_bf16 v[100:103], v[136:139], v[152:155], v[100:103]
	v_mfma_f32_16x16x32_bf16 v[92:95], v[128:131], v[160:163], v[92:95]
	v_mfma_f32_16x16x32_bf16 v[84:87], v[136:139], v[160:163], v[84:87]
	v_mfma_f32_16x16x32_bf16 v[76:79], v[128:131], v[168:171], v[76:79]
	v_mfma_f32_16x16x32_bf16 v[68:71], v[136:139], v[168:171], v[68:71]
	v_mfma_f32_16x16x32_bf16 v[124:127], v[132:135], v[148:151], v[124:127]
	v_mfma_f32_16x16x32_bf16 v[116:119], v[140:143], v[148:151], v[116:119]
	v_mfma_f32_16x16x32_bf16 v[108:111], v[132:135], v[156:159], v[108:111]
	v_mfma_f32_16x16x32_bf16 v[100:103], v[140:143], v[156:159], v[100:103]
	v_mfma_f32_16x16x32_bf16 v[92:95], v[132:135], v[164:167], v[92:95]
	v_mfma_f32_16x16x32_bf16 v[84:87], v[140:143], v[164:167], v[84:87]
	v_mfma_f32_16x16x32_bf16 v[76:79], v[132:135], v[172:175], v[76:79]
	v_mfma_f32_16x16x32_bf16 v[68:71], v[140:143], v[172:175], v[68:71]
	v_mfma_f32_16x16x32_bf16 v[120:123], v[188:191], v[144:147], v[120:123]
	v_mfma_f32_16x16x32_bf16 v[112:115], v[200:203], v[144:147], v[112:115]
	v_mfma_f32_16x16x32_bf16 v[104:107], v[188:191], v[152:155], v[104:107]
	v_mfma_f32_16x16x32_bf16 v[96:99], v[200:203], v[152:155], v[96:99]
	v_mfma_f32_16x16x32_bf16 v[88:91], v[188:191], v[160:163], v[88:91]
	v_mfma_f32_16x16x32_bf16 v[80:83], v[200:203], v[160:163], v[80:83]
	v_mfma_f32_16x16x32_bf16 v[72:75], v[188:191], v[168:171], v[72:75]
	v_mfma_f32_16x16x32_bf16 v[64:67], v[200:203], v[168:171], v[64:67]
	v_mfma_f32_16x16x32_bf16 v[120:123], v[196:199], v[148:151], v[120:123]
	v_mfma_f32_16x16x32_bf16 v[112:115], v[218:221], v[148:151], v[112:115]
	v_mfma_f32_16x16x32_bf16 v[104:107], v[196:199], v[156:159], v[104:107]
	v_mfma_f32_16x16x32_bf16 v[96:99], v[218:221], v[156:159], v[96:99]
	v_mfma_f32_16x16x32_bf16 v[88:91], v[196:199], v[164:167], v[88:91]
	v_mfma_f32_16x16x32_bf16 v[80:83], v[218:221], v[164:167], v[80:83]
	v_mfma_f32_16x16x32_bf16 v[72:75], v[196:199], v[172:175], v[72:75]
	v_mfma_f32_16x16x32_bf16 v[64:67], v[218:221], v[172:175], v[64:67]
	s_barrier
	s_add_u32 s76, s44, 0x80
	s_addc_u32 s77, s45, 0
	ds_read_b128 v[144:147], v216 offset:49152
	ds_read_b128 v[148:151], v216 offset:50176
	ds_read_b128 v[152:155], v216 offset:51200
	ds_read_b128 v[156:159], v216 offset:52224
	s_add_i32 m0, s92, 0x18000
	ds_read_b128 v[160:163], v216 offset:53248
	ds_read_b128 v[164:167], v216 offset:54272
	ds_read_b128 v[168:171], v216 offset:55296
	ds_read_b128 v[172:175], v216 offset:56320
	global_load_lds_dwordx4 v192, s[76:77]
	s_add_i32 m0, s92, 0x1a000
	s_nop 0
	global_load_lds_dwordx4 v180, s[76:77]
	s_add_u32 s76, s44, 0x80080
	s_addc_u32 s77, s45, 0
	s_add_i32 m0, s92, 0x1c000
	s_nop 0
	global_load_lds_dwordx4 v192, s[76:77]
	s_add_i32 m0, s92, 0x1e000
	s_nop 0
	global_load_lds_dwordx4 v180, s[76:77]
	s_waitcnt vmcnt(4)
	s_waitcnt lgkmcnt(0)
	s_barrier
	v_mfma_f32_16x16x32_bf16 v[60:63], v[128:131], v[144:147], v[60:63]
	v_mfma_f32_16x16x32_bf16 v[52:55], v[136:139], v[144:147], v[52:55]
	v_mfma_f32_16x16x32_bf16 v[44:47], v[128:131], v[152:155], v[44:47]
	v_mfma_f32_16x16x32_bf16 v[36:39], v[136:139], v[152:155], v[36:39]
	v_mfma_f32_16x16x32_bf16 v[28:31], v[128:131], v[160:163], v[28:31]
	v_mfma_f32_16x16x32_bf16 v[20:23], v[136:139], v[160:163], v[20:23]
	v_mfma_f32_16x16x32_bf16 v[12:15], v[128:131], v[168:171], v[12:15]
	v_mfma_f32_16x16x32_bf16 v[4:7], v[136:139], v[168:171], v[4:7]
	v_mfma_f32_16x16x32_bf16 v[60:63], v[132:135], v[148:151], v[60:63]
	v_mfma_f32_16x16x32_bf16 v[52:55], v[140:143], v[148:151], v[52:55]
	v_mfma_f32_16x16x32_bf16 v[44:47], v[132:135], v[156:159], v[44:47]
	v_mfma_f32_16x16x32_bf16 v[36:39], v[140:143], v[156:159], v[36:39]
	v_mfma_f32_16x16x32_bf16 v[28:31], v[132:135], v[164:167], v[28:31]
	v_mfma_f32_16x16x32_bf16 v[20:23], v[140:143], v[164:167], v[20:23]
	v_mfma_f32_16x16x32_bf16 v[12:15], v[132:135], v[172:175], v[12:15]
	v_mfma_f32_16x16x32_bf16 v[4:7], v[140:143], v[172:175], v[4:7]
	v_mfma_f32_16x16x32_bf16 v[56:59], v[188:191], v[144:147], v[56:59]
	v_mfma_f32_16x16x32_bf16 v[48:51], v[200:203], v[144:147], v[48:51]
	v_mfma_f32_16x16x32_bf16 v[40:43], v[188:191], v[152:155], v[40:43]
	v_mfma_f32_16x16x32_bf16 v[32:35], v[200:203], v[152:155], v[32:35]
	v_mfma_f32_16x16x32_bf16 v[24:27], v[188:191], v[160:163], v[24:27]
	v_mfma_f32_16x16x32_bf16 v[16:19], v[200:203], v[160:163], v[16:19]
	v_mfma_f32_16x16x32_bf16 v[8:11], v[188:191], v[168:171], v[8:11]
	v_mfma_f32_16x16x32_bf16 v[0:3], v[200:203], v[168:171], v[0:3]
	v_mfma_f32_16x16x32_bf16 v[56:59], v[196:199], v[148:151], v[56:59]
	v_mfma_f32_16x16x32_bf16 v[48:51], v[218:221], v[148:151], v[48:51]
	v_mfma_f32_16x16x32_bf16 v[40:43], v[196:199], v[156:159], v[40:43]
	v_mfma_f32_16x16x32_bf16 v[32:35], v[218:221], v[156:159], v[32:35]
	v_mfma_f32_16x16x32_bf16 v[24:27], v[196:199], v[164:167], v[24:27]
	v_mfma_f32_16x16x32_bf16 v[16:19], v[218:221], v[164:167], v[16:19]
	v_mfma_f32_16x16x32_bf16 v[8:11], v[196:199], v[172:175], v[8:11]
	v_mfma_f32_16x16x32_bf16 v[0:3], v[218:221], v[172:175], v[0:3]
	s_add_i32 s69, s69, 2
	s_add_u32 s40, s40, 0x100
	s_addc_u32 s41, s41, 0
	s_add_u32 s9, s9, 0x100
	s_addc_u32 s15, s15, 0
	s_cmp_gt_u32 s69, 29
	s_barrier
	s_cbranch_scc0 .LBB0_101
	s_cmp_lt_i32 s75, 8
	s_mov_b32 s9, 1
	s_cbranch_scc1 .LBB0_110
	s_sub_i32 s4, s75, 30
	s_cmp_lt_u32 s4, 4
	s_mov_b32 s9, 2
	s_cbranch_scc1 .LBB0_110
	s_and_b32 s9, s75, 0x7ffffffc
	s_cmp_lt_i32 s9, 20
	s_cbranch_scc1 .LBB0_106
	s_cmp_lg_u32 s9, 20
	s_cselect_b64 s[4:5], -1, 0
	s_cbranch_execz .LBB0_107
	s_branch .LBB0_108

; #define PG8_STAGE(bufoff, gbase, voff) do { _Pragma("unroll") for (int _i = 0; _i < 2; ++_i) \
;         __builtin_amdgcn_global_load_lds((const unsigned*)((const char*)(gbase) + (voff)[_i]), (LAS unsigned*)(lds + (bufoff) + ldsw + _i * 8192), 16, 0, 0); } while (0)
; #define PG8_LDA(dst, b, h) do { _Pragma("unroll") for (int m = 0; m < 4; ++m) _Pragma("unroll") for (int k = 0; k < 2; ++k) dst[m][k] = *(const LAS bf16x8*)(lds + PG8_SA(b, h) + aoff + m * 2048 + k * 1024); } while (0)
; #define PG8_LDB(dst, b, h) do { _Pragma("unroll") for (int n = 0; n < 2; ++n) _Pragma("unroll") for (int k = 0; k < 2; ++k) dst[n][k] = *(const LAS bf16x8*)(lds + PG8_SB(b, h) + boff + n * 2048 + k * 1024); } while (0)
; #define PG8_MMA(ai, bj, At, Bt) do { __builtin_amdgcn_s_setprio(1); _Pragma("unroll") for (int m = 0; m < 4; ++m) _Pragma("unroll") for (int n = 0; n < 2; ++n) _Pragma("unroll") for (int k = 0; k < 2; ++k) \
;         acc[ai][bj][m][n] = __builtin_amdgcn_mfma_f32_16x16x32_bf16(Bt[n][k], At[m][k], acc[ai][bj][m][n], 0, 0, 0); __builtin_amdgcn_s_setprio(0); } while (0)
; #define PG8_BAR __builtin_amdgcn_s_barrier()
; template <class Prog>
; __device__ __forceinline__ void gemm_phase(LAS unsigned char* lds, const int K, const Prog& S) {
;     ...
;     for (;;) {
;         const bool has_next = S.next(ui + 1, nxt);
;         const char* nA = has_next ? nxt.a : cA; const char* nB = has_next ? nxt.b : cB;
;         for (int t = 0; t < nt; t += 2) {
;             const bool last = (t == nt - 2);
;             const char* a1 = cA + (size_t)(t + 1) * kstep;
;             const char* a2 = last ? nA : cA + (size_t)(t + 2) * kstep; const char* b2 = last ? nB : cB + (size_t)(t + 2) * kstep;
;             const char* a3 = a2 + kstep; const char* b3 = b2 + kstep;
;             PG8_LDB(B0, 0, 0); PG8_SCHED; PG8_LDA(At, 0, 0); PG8_STAGE(PG8_SA(1, 1), a1 + hstep, voffA);
;             PG8_WAIT_L(8); PG8_BAR; PG8_WAIT_L(0); PG8_MMA(0, 0, At, B0); PG8_BAR; PG8_SCHED;
;             PG8_LDB(B1, 0, 1); PG8_STAGE(PG8_SB(0, 0), b2, voffB);
;             PG8_BAR; PG8_WAIT_L(0); PG8_MMA(0, 1, At, B1); PG8_BAR;
;             PG8_LDA(At, 0, 1); PG8_STAGE(PG8_SA(0, 0), a2, voffA);
;             PG8_BAR; PG8_WAIT_L(0); PG8_MMA(1, 0, At, B0); PG8_BAR; PG8_SCHED;
;             PG8_STAGE(PG8_SB(0, 1), b2 + hstep, voffB);
;             PG8_WAIT_V(6); PG8_BAR; PG8_MMA(1, 1, At, B1); PG8_BAR;
.LBB0_399:
	s_add_u32 s44, s44, 0x40080
	s_addc_u32 s45, s45, 0
	s_add_u32 s41, s46, 0x100
	s_addc_u32 s43, s47, 0
	s_mov_b32 s55, -2
	v_add_u32_e32 v206, 0x10000, v245
	.p2align 6
.LBB0_400:
	s_add_u32 s46, s44, 0xfffc0080
	s_addc_u32 s47, s45, -1
	s_cmp_eq_u32 s55, 12
	s_cselect_b32 s53, s7, s47
	s_cselect_b32 s52, s6, s46
	s_cselect_b32 s47, s9, s43
	s_cselect_b32 s46, s8, s41
	s_add_u32 s84, s44, 0xfffc0000
	s_addc_u32 s85, s45, -1
	ds_read_b128 v[128:131], v206
	ds_read_b128 v[132:135], v206 offset:1024
	ds_read_b128 v[136:139], v206 offset:2048
	ds_read_b128 v[140:143], v206 offset:3072
	s_add_i32 m0, s74, 0x8000
	ds_read_b128 v[176:179], v206 offset:16384
	ds_read_b128 v[180:183], v206 offset:17408
	ds_read_b128 v[184:187], v206 offset:18432
	ds_read_b128 v[188:191], v206 offset:19456
	global_load_lds_dwordx4 v202, s[84:85]
	s_add_i32 m0, s74, 0xa000
	ds_read_b128 v[144:147], v247
	ds_read_b128 v[148:151], v247 offset:1024
	ds_read_b128 v[152:155], v247 offset:2048
	ds_read_b128 v[156:159], v247 offset:3072
	global_load_lds_dwordx4 v204, s[84:85]
	s_add_i32 m0, s74, 0xc000
	ds_read_b128 v[160:163], v247 offset:4096
	ds_read_b128 v[164:167], v247 offset:5120
	ds_read_b128 v[168:171], v247 offset:6144
	ds_read_b128 v[172:175], v247 offset:7168
	global_load_lds_dwordx4 v202, s[44:45]
	s_add_i32 m0, s74, 0xe000
	s_nop 0
	global_load_lds_dwordx4 v204, s[44:45]
	s_waitcnt lgkmcnt(0)
	s_barrier
	v_mfma_f32_16x16x32_bf16 v[124:127], v[128:131], v[144:147], v[124:127]
	v_mfma_f32_16x16x32_bf16 v[120:123], v[136:139], v[144:147], v[120:123]
	v_mfma_f32_16x16x32_bf16 v[116:119], v[128:131], v[152:155], v[116:119]
	v_mfma_f32_16x16x32_bf16 v[112:115], v[136:139], v[152:155], v[112:115]
	v_mfma_f32_16x16x32_bf16 v[108:111], v[128:131], v[160:163], v[108:111]
	v_mfma_f32_16x16x32_bf16 v[104:107], v[136:139], v[160:163], v[104:107]
	v_mfma_f32_16x16x32_bf16 v[100:103], v[128:131], v[168:171], v[100:103]
	v_mfma_f32_16x16x32_bf16 v[96:99], v[136:139], v[168:171], v[96:99]
	v_mfma_f32_16x16x32_bf16 v[124:127], v[132:135], v[148:151], v[124:127]
	v_mfma_f32_16x16x32_bf16 v[120:123], v[140:143], v[148:151], v[120:123]
	v_mfma_f32_16x16x32_bf16 v[116:119], v[132:135], v[156:159], v[116:119]
	v_mfma_f32_16x16x32_bf16 v[112:115], v[140:143], v[156:159], v[112:115]
	v_mfma_f32_16x16x32_bf16 v[108:111], v[132:135], v[164:167], v[108:111]
	v_mfma_f32_16x16x32_bf16 v[104:107], v[140:143], v[164:167], v[104:107]
	v_mfma_f32_16x16x32_bf16 v[100:103], v[132:135], v[172:175], v[100:103]
	v_mfma_f32_16x16x32_bf16 v[96:99], v[140:143], v[172:175], v[96:99]
	v_mfma_f32_16x16x32_bf16 v[92:95], v[176:179], v[144:147], v[92:95]
	v_mfma_f32_16x16x32_bf16 v[88:91], v[184:187], v[144:147], v[88:91]
	v_mfma_f32_16x16x32_bf16 v[84:87], v[176:179], v[152:155], v[84:87]
	v_mfma_f32_16x16x32_bf16 v[80:83], v[184:187], v[152:155], v[80:83]
	v_mfma_f32_16x16x32_bf16 v[76:79], v[176:179], v[160:163], v[76:79]
	v_mfma_f32_16x16x32_bf16 v[72:75], v[184:187], v[160:163], v[72:75]
	v_mfma_f32_16x16x32_bf16 v[68:71], v[176:179], v[168:171], v[68:71]
	v_mfma_f32_16x16x32_bf16 v[64:67], v[184:187], v[168:171], v[64:67]
	v_mfma_f32_16x16x32_bf16 v[92:95], v[180:183], v[148:151], v[92:95]
	v_mfma_f32_16x16x32_bf16 v[88:91], v[188:191], v[148:151], v[88:91]
	v_mfma_f32_16x16x32_bf16 v[84:87], v[180:183], v[156:159], v[84:87]
	v_mfma_f32_16x16x32_bf16 v[80:83], v[188:191], v[156:159], v[80:83]
	v_mfma_f32_16x16x32_bf16 v[76:79], v[180:183], v[164:167], v[76:79]
	v_mfma_f32_16x16x32_bf16 v[72:75], v[188:191], v[164:167], v[72:75]
	v_mfma_f32_16x16x32_bf16 v[68:71], v[180:183], v[172:175], v[68:71]
	v_mfma_f32_16x16x32_bf16 v[64:67], v[188:191], v[172:175], v[64:67]
	s_barrier
	ds_read_b128 v[144:147], v247 offset:16384
	ds_read_b128 v[148:151], v247 offset:17408
	ds_read_b128 v[152:155], v247 offset:18432
	ds_read_b128 v[156:159], v247 offset:19456
	s_add_i32 m0, s74, 0x10000
	ds_read_b128 v[160:163], v247 offset:20480
	ds_read_b128 v[164:167], v247 offset:21504
	ds_read_b128 v[168:171], v247 offset:22528
	ds_read_b128 v[172:175], v247 offset:23552
	global_load_lds_dwordx4 v192, s[46:47]
	s_add_i32 m0, s74, 0x12000
	s_nop 0
	global_load_lds_dwordx4 v200, s[46:47]
	s_add_u32 s84, s46, 0x40000
	s_addc_u32 s85, s47, 0
	s_add_i32 m0, s74, 0x14000
	s_nop 0
	global_load_lds_dwordx4 v192, s[84:85]
	s_add_i32 m0, s74, 0x16000
	s_nop 0
	global_load_lds_dwordx4 v200, s[84:85]
	s_waitcnt vmcnt(4)
	s_waitcnt lgkmcnt(0)
	s_barrier
	v_mfma_f32_16x16x32_bf16 v[60:63], v[128:131], v[144:147], v[60:63]
	v_mfma_f32_16x16x32_bf16 v[56:59], v[136:139], v[144:147], v[56:59]
	v_mfma_f32_16x16x32_bf16 v[52:55], v[128:131], v[152:155], v[52:55]
	v_mfma_f32_16x16x32_bf16 v[48:51], v[136:139], v[152:155], v[48:51]
	v_mfma_f32_16x16x32_bf16 v[44:47], v[128:131], v[160:163], v[44:47]
	v_mfma_f32_16x16x32_bf16 v[40:43], v[136:139], v[160:163], v[40:43]
	v_mfma_f32_16x16x32_bf16 v[36:39], v[128:131], v[168:171], v[36:39]
	v_mfma_f32_16x16x32_bf16 v[32:35], v[136:139], v[168:171], v[32:35]
	v_mfma_f32_16x16x32_bf16 v[60:63], v[132:135], v[148:151], v[60:63]
	v_mfma_f32_16x16x32_bf16 v[56:59], v[140:143], v[148:151], v[56:59]
	v_mfma_f32_16x16x32_bf16 v[52:55], v[132:135], v[156:159], v[52:55]
	v_mfma_f32_16x16x32_bf16 v[48:51], v[140:143], v[156:159], v[48:51]
	v_mfma_f32_16x16x32_bf16 v[44:47], v[132:135], v[164:167], v[44:47]
	v_mfma_f32_16x16x32_bf16 v[40:43], v[140:143], v[164:167], v[40:43]
	v_mfma_f32_16x16x32_bf16 v[36:39], v[132:135], v[172:175], v[36:39]
	v_mfma_f32_16x16x32_bf16 v[32:35], v[140:143], v[172:175], v[32:35]
	v_mfma_f32_16x16x32_bf16 v[28:31], v[176:179], v[144:147], v[28:31]
	v_mfma_f32_16x16x32_bf16 v[24:27], v[184:187], v[144:147], v[24:27]
	v_mfma_f32_16x16x32_bf16 v[20:23], v[176:179], v[152:155], v[20:23]
	v_mfma_f32_16x16x32_bf16 v[16:19], v[184:187], v[152:155], v[16:19]
	v_mfma_f32_16x16x32_bf16 v[12:15], v[176:179], v[160:163], v[12:15]
	v_mfma_f32_16x16x32_bf16 v[8:11], v[184:187], v[160:163], v[8:11]
	v_mfma_f32_16x16x32_bf16 v[4:7], v[176:179], v[168:171], v[4:7]
	v_mfma_f32_16x16x32_bf16 v[0:3], v[184:187], v[168:171], v[0:3]
	v_mfma_f32_16x16x32_bf16 v[28:31], v[180:183], v[148:151], v[28:31]
	v_mfma_f32_16x16x32_bf16 v[24:27], v[188:191], v[148:151], v[24:27]
	v_mfma_f32_16x16x32_bf16 v[20:23], v[180:183], v[156:159], v[20:23]
	v_mfma_f32_16x16x32_bf16 v[16:19], v[188:191], v[156:159], v[16:19]
	v_mfma_f32_16x16x32_bf16 v[12:15], v[180:183], v[164:167], v[12:15]
	v_mfma_f32_16x16x32_bf16 v[8:11], v[188:191], v[164:167], v[8:11]
	v_mfma_f32_16x16x32_bf16 v[4:7], v[180:183], v[172:175], v[4:7]
	v_mfma_f32_16x16x32_bf16 v[0:3], v[188:191], v[172:175], v[0:3]
	s_barrier
; #define PG8_STAGE(bufoff, gbase, voff) do { _Pragma("unroll") for (int _i = 0; _i < 2; ++_i) \
;         __builtin_amdgcn_global_load_lds((const unsigned*)((const char*)(gbase) + (voff)[_i]), (LAS unsigned*)(lds + (bufoff) + ldsw + _i * 8192), 16, 0, 0); } while (0)
; #define PG8_LDA(dst, b, h) do { _Pragma("unroll") for (int m = 0; m < 4; ++m) _Pragma("unroll") for (int k = 0; k < 2; ++k) dst[m][k] = *(const LAS bf16x8*)(lds + PG8_SA(b, h) + aoff + m * 2048 + k * 1024); } while (0)
; #define PG8_LDB(dst, b, h) do { _Pragma("unroll") for (int n = 0; n < 2; ++n) _Pragma("unroll") for (int k = 0; k < 2; ++k) dst[n][k] = *(const LAS bf16x8*)(lds + PG8_SB(b, h) + boff + n * 2048 + k * 1024); } while (0)
; #define PG8_MMA(ai, bj, At, Bt) do { __builtin_amdgcn_s_setprio(1); _Pragma("unroll") for (int m = 0; m < 4; ++m) _Pragma("unroll") for (int n = 0; n < 2; ++n) _Pragma("unroll") for (int k = 0; k < 2; ++k) \
;         acc[ai][bj][m][n] = __builtin_amdgcn_mfma_f32_16x16x32_bf16(Bt[n][k], At[m][k], acc[ai][bj][m][n], 0, 0, 0); __builtin_amdgcn_s_setprio(0); } while (0)
; #define PG8_WAIT_L(n) asm volatile("s_waitcnt lgkmcnt(" #n ")" ::: "memory")
; #define PG8_BAR __builtin_amdgcn_s_barrier()
; #define PG8_SCHED __builtin_amdgcn_sched_barrier(0)
; template <class Prog>
; __device__ __forceinline__ void gemm_phase(LAS unsigned char* lds, const int K, const Prog& S) {
;     ...
;             PG8_LDB(B0, 1, 0); PG8_SCHED; PG8_LDA(At, 1, 0); PG8_STAGE(PG8_SA(0, 1), a2 + hstep, voffA);
;             PG8_WAIT_L(8); PG8_BAR; PG8_WAIT_L(0); PG8_MMA(0, 0, At, B0); PG8_BAR; PG8_SCHED;
;             PG8_LDB(B1, 1, 1); PG8_STAGE(PG8_SB(1, 0), b3, voffB);
;             PG8_BAR; PG8_WAIT_L(0); PG8_MMA(0, 1, At, B1); PG8_BAR;
	s_add_u32 s84, s52, 0x40000
	s_addc_u32 s85, s53, 0
	ds_read_b128 v[128:131], v206 offset:32768
	ds_read_b128 v[132:135], v206 offset:33792
	ds_read_b128 v[136:139], v206 offset:34816
	ds_read_b128 v[140:143], v206 offset:35840
	s_mov_b32 m0, s74
	ds_read_b128 v[176:179], v206 offset:49152
	ds_read_b128 v[180:183], v206 offset:50176
	ds_read_b128 v[184:187], v206 offset:51200
	ds_read_b128 v[188:191], v206 offset:52224
	global_load_lds_dwordx4 v196, s[52:53]
	s_add_i32 m0, s74, 0x2000
	ds_read_b128 v[144:147], v247 offset:32768
	ds_read_b128 v[148:151], v247 offset:33792
	ds_read_b128 v[152:155], v247 offset:34816
	ds_read_b128 v[156:159], v247 offset:35840
	global_load_lds_dwordx4 v198, s[52:53]
	s_add_i32 m0, s74, 0x4000
	ds_read_b128 v[160:163], v247 offset:36864
	ds_read_b128 v[164:167], v247 offset:37888
	ds_read_b128 v[168:171], v247 offset:38912
	ds_read_b128 v[172:175], v247 offset:39936
	global_load_lds_dwordx4 v196, s[84:85]
	s_add_i32 m0, s74, 0x6000
	s_nop 0
	global_load_lds_dwordx4 v198, s[84:85]
	s_waitcnt lgkmcnt(0)
	s_barrier
	v_mfma_f32_16x16x32_bf16 v[124:127], v[128:131], v[144:147], v[124:127]
	v_mfma_f32_16x16x32_bf16 v[120:123], v[136:139], v[144:147], v[120:123]
	v_mfma_f32_16x16x32_bf16 v[116:119], v[128:131], v[152:155], v[116:119]
	v_mfma_f32_16x16x32_bf16 v[112:115], v[136:139], v[152:155], v[112:115]
	v_mfma_f32_16x16x32_bf16 v[108:111], v[128:131], v[160:163], v[108:111]
	v_mfma_f32_16x16x32_bf16 v[104:107], v[136:139], v[160:163], v[104:107]
	v_mfma_f32_16x16x32_bf16 v[100:103], v[128:131], v[168:171], v[100:103]
	v_mfma_f32_16x16x32_bf16 v[96:99], v[136:139], v[168:171], v[96:99]
	v_mfma_f32_16x16x32_bf16 v[124:127], v[132:135], v[148:151], v[124:127]
	v_mfma_f32_16x16x32_bf16 v[120:123], v[140:143], v[148:151], v[120:123]
	v_mfma_f32_16x16x32_bf16 v[116:119], v[132:135], v[156:159], v[116:119]
	v_mfma_f32_16x16x32_bf16 v[112:115], v[140:143], v[156:159], v[112:115]
	v_mfma_f32_16x16x32_bf16 v[108:111], v[132:135], v[164:167], v[108:111]
	v_mfma_f32_16x16x32_bf16 v[104:107], v[140:143], v[164:167], v[104:107]
	v_mfma_f32_16x16x32_bf16 v[100:103], v[132:135], v[172:175], v[100:103]
	v_mfma_f32_16x16x32_bf16 v[96:99], v[140:143], v[172:175], v[96:99]
	v_mfma_f32_16x16x32_bf16 v[92:95], v[176:179], v[144:147], v[92:95]
	v_mfma_f32_16x16x32_bf16 v[88:91], v[184:187], v[144:147], v[88:91]
	v_mfma_f32_16x16x32_bf16 v[84:87], v[176:179], v[152:155], v[84:87]
	v_mfma_f32_16x16x32_bf16 v[80:83], v[184:187], v[152:155], v[80:83]
	v_mfma_f32_16x16x32_bf16 v[76:79], v[176:179], v[160:163], v[76:79]
	v_mfma_f32_16x16x32_bf16 v[72:75], v[184:187], v[160:163], v[72:75]
	v_mfma_f32_16x16x32_bf16 v[68:71], v[176:179], v[168:171], v[68:71]
	v_mfma_f32_16x16x32_bf16 v[64:67], v[184:187], v[168:171], v[64:67]
	v_mfma_f32_16x16x32_bf16 v[92:95], v[180:183], v[148:151], v[92:95]
	v_mfma_f32_16x16x32_bf16 v[88:91], v[188:191], v[148:151], v[88:91]
	v_mfma_f32_16x16x32_bf16 v[84:87], v[180:183], v[156:159], v[84:87]
	v_mfma_f32_16x16x32_bf16 v[80:83], v[188:191], v[156:159], v[80:83]
	v_mfma_f32_16x16x32_bf16 v[76:79], v[180:183], v[164:167], v[76:79]
	v_mfma_f32_16x16x32_bf16 v[72:75], v[188:191], v[164:167], v[72:75]
	v_mfma_f32_16x16x32_bf16 v[68:71], v[180:183], v[172:175], v[68:71]
	v_mfma_f32_16x16x32_bf16 v[64:67], v[188:191], v[172:175], v[64:67]
	s_barrier
; #define PG8_STAGE(bufoff, gbase, voff) do { _Pragma("unroll") for (int _i = 0; _i < 2; ++_i) \
;         __builtin_amdgcn_global_load_lds((const unsigned*)((const char*)(gbase) + (voff)[_i]), (LAS unsigned*)(lds + (bufoff) + ldsw + _i * 8192), 16, 0, 0); } while (0)
; #define PG8_LDA(dst, b, h) do { _Pragma("unroll") for (int m = 0; m < 4; ++m) _Pragma("unroll") for (int k = 0; k < 2; ++k) dst[m][k] = *(const LAS bf16x8*)(lds + PG8_SA(b, h) + aoff + m * 2048 + k * 1024); } while (0)
; #define PG8_MMA(ai, bj, At, Bt) do { __builtin_amdgcn_s_setprio(1); _Pragma("unroll") for (int m = 0; m < 4; ++m) _Pragma("unroll") for (int n = 0; n < 2; ++n) _Pragma("unroll") for (int k = 0; k < 2; ++k) \
;         acc[ai][bj][m][n] = __builtin_amdgcn_mfma_f32_16x16x32_bf16(Bt[n][k], At[m][k], acc[ai][bj][m][n], 0, 0, 0); __builtin_amdgcn_s_setprio(0); } while (0)
; #define PG8_WAIT_V(n) asm volatile("s_waitcnt vmcnt(" #n ")" ::: "memory")
; #define PG8_WAIT_L(n) asm volatile("s_waitcnt lgkmcnt(" #n ")" ::: "memory")
; #define PG8_BAR __builtin_amdgcn_s_barrier()
; #define PG8_SCHED __builtin_amdgcn_sched_barrier(0)
; template <class Prog>
; __device__ __forceinline__ void gemm_phase(LAS unsigned char* lds, const int K, const Prog& S) {
;     ...
;             PG8_LDA(At, 1, 1); PG8_STAGE(PG8_SA(1, 0), a3, voffA);
;             PG8_BAR; PG8_WAIT_L(0); PG8_MMA(1, 0, At, B0); PG8_BAR; PG8_SCHED;
;             PG8_STAGE(PG8_SB(1, 1), b3 + hstep, voffB);
;             PG8_WAIT_V(6); PG8_BAR; PG8_MMA(1, 1, At, B1); PG8_BAR;
;         }
;         S.epi(acc, cur, wr, wc, fr, fq);
;     __device__ __forceinline__ void epi(f32x4 (&acc)[2][2][4][2], const pg8::Unit& u, int wr, int wc, int fr, int fq) const {
;     ...
;         const int dsub = sub < 2 ? sub + 1 : sub;
	s_add_u32 s84, s46, 0x80
	s_addc_u32 s85, s47, 0
	ds_read_b128 v[144:147], v247 offset:49152
	ds_read_b128 v[148:151], v247 offset:50176
	ds_read_b128 v[152:155], v247 offset:51200
	ds_read_b128 v[156:159], v247 offset:52224
	s_add_i32 m0, s74, 0x18000
	ds_read_b128 v[160:163], v247 offset:53248
	ds_read_b128 v[164:167], v247 offset:54272
	ds_read_b128 v[168:171], v247 offset:55296
	ds_read_b128 v[172:175], v247 offset:56320
	global_load_lds_dwordx4 v192, s[84:85]
	s_add_i32 m0, s74, 0x1a000
	s_nop 0
	global_load_lds_dwordx4 v200, s[84:85]
	s_add_u32 s84, s46, 0x40080
	s_addc_u32 s85, s47, 0
	s_add_i32 m0, s74, 0x1c000
	s_nop 0
	global_load_lds_dwordx4 v192, s[84:85]
	s_add_i32 m0, s74, 0x1e000
	s_nop 0
	global_load_lds_dwordx4 v200, s[84:85]
	s_waitcnt vmcnt(4)
	s_waitcnt lgkmcnt(0)
	s_barrier
	v_mfma_f32_16x16x32_bf16 v[60:63], v[128:131], v[144:147], v[60:63]
	v_mfma_f32_16x16x32_bf16 v[56:59], v[136:139], v[144:147], v[56:59]
	v_mfma_f32_16x16x32_bf16 v[52:55], v[128:131], v[152:155], v[52:55]
	v_mfma_f32_16x16x32_bf16 v[48:51], v[136:139], v[152:155], v[48:51]
	v_mfma_f32_16x16x32_bf16 v[44:47], v[128:131], v[160:163], v[44:47]
	v_mfma_f32_16x16x32_bf16 v[40:43], v[136:139], v[160:163], v[40:43]
	v_mfma_f32_16x16x32_bf16 v[36:39], v[128:131], v[168:171], v[36:39]
	v_mfma_f32_16x16x32_bf16 v[32:35], v[136:139], v[168:171], v[32:35]
	v_mfma_f32_16x16x32_bf16 v[60:63], v[132:135], v[148:151], v[60:63]
	v_mfma_f32_16x16x32_bf16 v[56:59], v[140:143], v[148:151], v[56:59]
	v_mfma_f32_16x16x32_bf16 v[52:55], v[132:135], v[156:159], v[52:55]
	v_mfma_f32_16x16x32_bf16 v[48:51], v[140:143], v[156:159], v[48:51]
	v_mfma_f32_16x16x32_bf16 v[44:47], v[132:135], v[164:167], v[44:47]
	v_mfma_f32_16x16x32_bf16 v[40:43], v[140:143], v[164:167], v[40:43]
	v_mfma_f32_16x16x32_bf16 v[36:39], v[132:135], v[172:175], v[36:39]
	v_mfma_f32_16x16x32_bf16 v[32:35], v[140:143], v[172:175], v[32:35]
	v_mfma_f32_16x16x32_bf16 v[28:31], v[176:179], v[144:147], v[28:31]
	v_mfma_f32_16x16x32_bf16 v[24:27], v[184:187], v[144:147], v[24:27]
	v_mfma_f32_16x16x32_bf16 v[20:23], v[176:179], v[152:155], v[20:23]
	v_mfma_f32_16x16x32_bf16 v[16:19], v[184:187], v[152:155], v[16:19]
	v_mfma_f32_16x16x32_bf16 v[12:15], v[176:179], v[160:163], v[12:15]
	v_mfma_f32_16x16x32_bf16 v[8:11], v[184:187], v[160:163], v[8:11]
	v_mfma_f32_16x16x32_bf16 v[4:7], v[176:179], v[168:171], v[4:7]
	v_mfma_f32_16x16x32_bf16 v[0:3], v[184:187], v[168:171], v[0:3]
	v_mfma_f32_16x16x32_bf16 v[28:31], v[180:183], v[148:151], v[28:31]
	v_mfma_f32_16x16x32_bf16 v[24:27], v[188:191], v[148:151], v[24:27]
	v_mfma_f32_16x16x32_bf16 v[20:23], v[180:183], v[156:159], v[20:23]
	v_mfma_f32_16x16x32_bf16 v[16:19], v[188:191], v[156:159], v[16:19]
	v_mfma_f32_16x16x32_bf16 v[12:15], v[180:183], v[164:167], v[12:15]
	v_mfma_f32_16x16x32_bf16 v[8:11], v[188:191], v[164:167], v[8:11]
	v_mfma_f32_16x16x32_bf16 v[4:7], v[180:183], v[172:175], v[4:7]
	v_mfma_f32_16x16x32_bf16 v[0:3], v[188:191], v[172:175], v[0:3]
	s_add_i32 s55, s55, 2
	s_add_u32 s44, s44, 0x100
	s_addc_u32 s45, s45, 0
	s_add_u32 s41, s41, 0x100
	s_addc_u32 s43, s43, 0
	s_cmp_gt_u32 s55, 13
	s_barrier
	s_cbranch_scc0 .LBB0_400
	s_cmp_lt_i32 s14, 2
	v_lshl_add_u32 v208, s15, 8, v244
	v_lshl_or_b32 v206, s54, 8, v246
	s_cselect_b64 s[8:9], -1, 0
	s_cmp_gt_i32 s14, 1
	v_mov_b64_e32 v[128:129], s[26:27]
	s_cselect_b64 s[92:93], -1, 0
	s_cmp_lg_u64 s[8:9], 0
	v_ashrrev_i32_e32 v207, 31, v206
	v_mad_i64_i32 v[128:129], s[6:7], v208, s58, v[128:129]
	s_addc_u32 s15, s14, 0
	s_lshl_b32 s46, s14, 11
	v_lshl_add_u64 v[128:129], v[206:207], 1, v[128:129]
	s_ashr_i32 s47, s46, 31
	v_lshl_add_u64 v[128:129], v[128:129], 0, s[34:35]
	v_lshl_add_u64 v[130:131], s[46:47], 1, v[128:129]
	global_load_dwordx4 v[188:191], v[130:131], off
	s_lshl_b32 s52, s15, 11
	s_ashr_i32 s53, s52, 31
	v_mov_b32_e32 v148, 0
	s_and_b64 vcc, exec, s[92:93]
	v_lshl_add_u64 v[128:129], s[52:53], 1, v[128:129]
	v_mov_b32_e32 v180, 0
	v_mov_b32_e32 v181, 0
	v_mov_b32_e32 v182, 0
	v_mov_b32_e32 v183, 0
	s_cbranch_vccnz .LBB0_403
	global_load_dwordx4 v[180:183], v[128:129], off

; #define PG8_STAGE(bufoff, gbase, voff) do { _Pragma("unroll") for (int _i = 0; _i < 2; ++_i) \
;         __builtin_amdgcn_global_load_lds((const unsigned*)((const char*)(gbase) + (voff)[_i]), (LAS unsigned*)(lds + (bufoff) + ldsw + _i * 8192), 16, 0, 0); } while (0)
; #define PG8_LDA(dst, b, h) do { _Pragma("unroll") for (int m = 0; m < 4; ++m) _Pragma("unroll") for (int k = 0; k < 2; ++k) dst[m][k] = *(const LAS bf16x8*)(lds + PG8_SA(b, h) + aoff + m * 2048 + k * 1024); } while (0)
; #define PG8_WAIT_V(n) asm volatile("s_waitcnt vmcnt(" #n ")" ::: "memory")
; #define PG8_WAIT_L(n) asm volatile("s_waitcnt lgkmcnt(" #n ")" ::: "memory")
; template <class Prog>
; __device__ __forceinline__ void gemm_phase(LAS unsigned char* lds, const int K, const Prog& S) {
;     ...
;     Unit cur, nxt; int ui = 0;
;     if (!S.next(0, cur)) return;
;     f32x4 acc[2][2][4][2];
; #pragma unroll
;     for (int a = 0; a < 2; ++a)
; #pragma unroll
;         for (int b = 0; b < 2; ++b)
; #pragma unroll
;             for (int m = 0; m < 4; ++m)
; #pragma unroll
;                 for (int n = 0; n < 2; ++n) acc[a][b][m][n] = (f32x4){0.f, 0.f, 0.f, 0.f};
;     bf16x8 At[4][2], B0[2][2], B1[2][2];
;     const char* cA = cur.a; const char* cB = cur.b;
;     PG8_STAGE(PG8_SB(0, 0), cB, voffB); PG8_STAGE(PG8_SA(0, 0), cA, voffA); PG8_STAGE(PG8_SB(0, 1), cB + hstep, voffB); PG8_STAGE(PG8_SA(0, 1), cA + hstep, voffA);
;     if (wr == 1) PG8_BAR;
;     PG8_WAIT_V(4); PG8_BAR;
;     PG8_STAGE(PG8_SB(1, 0), cB + kstep, voffB); PG8_STAGE(PG8_SA(1, 0), cA + kstep, voffA); PG8_STAGE(PG8_SB(1, 1), cB + hstep + kstep, voffB);
;     PG8_WAIT_V(6); PG8_BAR;
;     for (;;) {
;         const bool has_next = S.next(ui + 1, nxt);
;         const char* nA = has_next ? nxt.a : cA; const char* nB = has_next ? nxt.b : cB;
;         for (int t = 0; t < nt; t += 2) {
;             const bool last = (t == nt - 2);
;             const char* a1 = cA + (size_t)(t + 1) * kstep;
;             const char* a2 = last ? nA : cA + (size_t)(t + 2) * kstep; const char* b2 = last ? nB : cB + (size_t)(t + 2) * kstep;
;             const char* a3 = a2 + kstep; const char* b3 = b2 + kstep;
;             PG8_LDB(B0, 0, 0); PG8_SCHED; PG8_LDA(At, 0, 0); PG8_STAGE(PG8_SA(1, 1), a1 + hstep, voffA);
;             PG8_WAIT_L(8); PG8_BAR; PG8_WAIT_L(0); PG8_MMA(0, 0, At, B0); PG8_BAR; PG8_SCHED;
.LBB0_570:
	s_add_u32 s46, s46, 0x80080
	s_addc_u32 s47, s47, 0
	s_add_u32 s41, s52, 0x100
	v_mov_b32_e32 v0, 0
	s_addc_u32 s43, s53, 0
	s_mov_b32 s54, -2
	s_waitcnt lgkmcnt(0)
	v_mov_b32_e32 v1, v0
	v_mov_b32_e32 v2, v0
	v_mov_b32_e32 v3, v0
	v_mov_b32_e32 v4, v0
	v_mov_b32_e32 v5, v0
	v_mov_b32_e32 v6, v0
	v_mov_b32_e32 v7, v0
	v_mov_b32_e32 v16, v0
	v_mov_b32_e32 v17, v0
	v_mov_b32_e32 v18, v0
	v_mov_b32_e32 v19, v0
	v_mov_b32_e32 v20, v0
	v_mov_b32_e32 v21, v0
	v_mov_b32_e32 v22, v0
	v_mov_b32_e32 v23, v0
	v_mov_b32_e32 v32, v0
	v_mov_b32_e32 v33, v0
	v_mov_b32_e32 v34, v0
	v_mov_b32_e32 v35, v0
	v_mov_b32_e32 v36, v0
	v_mov_b32_e32 v37, v0
	v_mov_b32_e32 v38, v0
	v_mov_b32_e32 v39, v0
	v_mov_b32_e32 v48, v0
	v_mov_b32_e32 v49, v0
	v_mov_b32_e32 v50, v0
	v_mov_b32_e32 v51, v0
	v_mov_b32_e32 v52, v0
	v_mov_b32_e32 v53, v0
	v_mov_b32_e32 v54, v0
	v_mov_b32_e32 v55, v0
	v_mov_b32_e32 v8, v0
	v_mov_b32_e32 v9, v0
	v_mov_b32_e32 v10, v0
	v_mov_b32_e32 v11, v0
	v_mov_b32_e32 v12, v0
	v_mov_b32_e32 v13, v0
	v_mov_b32_e32 v14, v0
	v_mov_b32_e32 v15, v0
	s_waitcnt vmcnt(16)
	v_mov_b32_e32 v24, v0
	v_mov_b32_e32 v25, v0
	v_mov_b32_e32 v26, v0
	v_mov_b32_e32 v27, v0
	v_mov_b32_e32 v28, v0
	v_mov_b32_e32 v29, v0
	v_mov_b32_e32 v30, v0
	v_mov_b32_e32 v31, v0
	v_mov_b32_e32 v40, v0
	v_mov_b32_e32 v41, v0
	v_mov_b32_e32 v42, v0
	v_mov_b32_e32 v43, v0
	v_mov_b32_e32 v44, v0
	v_mov_b32_e32 v45, v0
	v_mov_b32_e32 v46, v0
	v_mov_b32_e32 v47, v0
	v_mov_b32_e32 v56, v0
	v_mov_b32_e32 v57, v0
	v_mov_b32_e32 v58, v0
	v_mov_b32_e32 v59, v0
	v_mov_b32_e32 v60, v0
	v_mov_b32_e32 v61, v0
	v_mov_b32_e32 v62, v0
	v_mov_b32_e32 v63, v0
	v_mov_b32_e32 v64, v0
	v_mov_b32_e32 v65, v0
	v_mov_b32_e32 v66, v0
	v_mov_b32_e32 v67, v0
	v_mov_b32_e32 v68, v0
	v_mov_b32_e32 v69, v0
	v_mov_b32_e32 v70, v0
	v_mov_b32_e32 v71, v0
	v_mov_b32_e32 v80, v0
	v_mov_b32_e32 v81, v0
	v_mov_b32_e32 v82, v0
	v_mov_b32_e32 v83, v0
	v_mov_b32_e32 v84, v0
	v_mov_b32_e32 v85, v0
	v_mov_b32_e32 v86, v0
	v_mov_b32_e32 v87, v0
	v_mov_b32_e32 v96, v0
	v_mov_b32_e32 v97, v0
	v_mov_b32_e32 v98, v0
	v_mov_b32_e32 v99, v0
	v_mov_b32_e32 v100, v0
	v_mov_b32_e32 v101, v0
	v_mov_b32_e32 v102, v0
	v_mov_b32_e32 v103, v0
	v_mov_b32_e32 v112, v0
	v_mov_b32_e32 v113, v0
	v_mov_b32_e32 v114, v0
	v_mov_b32_e32 v115, v0
	v_mov_b32_e32 v116, v0
	v_mov_b32_e32 v117, v0
	v_mov_b32_e32 v118, v0
	v_mov_b32_e32 v119, v0
	v_mov_b32_e32 v72, v0
	v_mov_b32_e32 v73, v0
	v_mov_b32_e32 v74, v0
	v_mov_b32_e32 v75, v0
	v_mov_b32_e32 v76, v0
	v_mov_b32_e32 v77, v0
	v_mov_b32_e32 v78, v0
	v_mov_b32_e32 v79, v0
	v_mov_b32_e32 v88, v0
	v_mov_b32_e32 v89, v0
	v_mov_b32_e32 v90, v0
	v_mov_b32_e32 v91, v0
	v_mov_b32_e32 v92, v0
	v_mov_b32_e32 v93, v0
	v_mov_b32_e32 v94, v0
	v_mov_b32_e32 v95, v0
	v_mov_b32_e32 v104, v0
	v_mov_b32_e32 v105, v0
	v_mov_b32_e32 v106, v0
	v_mov_b32_e32 v107, v0
	v_mov_b32_e32 v108, v0
	v_mov_b32_e32 v109, v0
	v_mov_b32_e32 v110, v0
	v_mov_b32_e32 v111, v0
	v_mov_b32_e32 v120, v0
	v_mov_b32_e32 v121, v0
	v_mov_b32_e32 v122, v0
	v_mov_b32_e32 v123, v0
	v_mov_b32_e32 v124, v0
	v_mov_b32_e32 v125, v0
	v_mov_b32_e32 v126, v0
	v_mov_b32_e32 v127, v0
	v_add_u32_e32 v202, 0x10000, v215
	.p2align 6
.LBB0_571:
	s_add_u32 s52, s46, 0xfff80080
	s_addc_u32 s53, s47, -1
	s_cmp_eq_u32 s54, 28
	s_cselect_b32 s93, s7, s53
	s_cselect_b32 s92, s6, s52
	s_cselect_b32 s53, s45, s43
	s_cselect_b32 s52, s44, s41
	s_add_u32 vcc_lo, s46, 0xfff80000
	s_addc_u32 vcc_hi, s47, -1
	ds_read_b128 v[128:131], v202
	ds_read_b128 v[132:135], v202 offset:1024
	ds_read_b128 v[136:139], v202 offset:2048
	ds_read_b128 v[140:143], v202 offset:3072
	s_add_i32 m0, s75, 0x8000
	ds_read_b128 v[176:179], v202 offset:16384
	ds_read_b128 v[180:183], v202 offset:17408
	ds_read_b128 v[184:187], v202 offset:18432
	ds_read_b128 v[198:201], v202 offset:19456
	global_load_lds_dwordx4 v190, vcc
	s_add_i32 m0, s75, 0xa000
	ds_read_b128 v[144:147], v217
	ds_read_b128 v[148:151], v217 offset:1024
	ds_read_b128 v[152:155], v217 offset:2048
	ds_read_b128 v[156:159], v217 offset:3072
	global_load_lds_dwordx4 v196, vcc
	s_add_i32 m0, s75, 0xc000
	ds_read_b128 v[160:163], v217 offset:4096
	ds_read_b128 v[164:167], v217 offset:5120
	ds_read_b128 v[168:171], v217 offset:6144
	ds_read_b128 v[172:175], v217 offset:7168
	global_load_lds_dwordx4 v190, s[46:47]
	s_add_i32 m0, s75, 0xe000
	s_nop 0
	global_load_lds_dwordx4 v196, s[46:47]
	s_waitcnt lgkmcnt(0)
	s_barrier
	v_mfma_f32_16x16x32_bf16 v[124:127], v[128:131], v[144:147], v[124:127]
	v_mfma_f32_16x16x32_bf16 v[120:123], v[136:139], v[144:147], v[120:123]
	v_mfma_f32_16x16x32_bf16 v[108:111], v[128:131], v[152:155], v[108:111]
	v_mfma_f32_16x16x32_bf16 v[104:107], v[136:139], v[152:155], v[104:107]
	v_mfma_f32_16x16x32_bf16 v[92:95], v[128:131], v[160:163], v[92:95]
	v_mfma_f32_16x16x32_bf16 v[88:91], v[136:139], v[160:163], v[88:91]
	v_mfma_f32_16x16x32_bf16 v[76:79], v[128:131], v[168:171], v[76:79]
	v_mfma_f32_16x16x32_bf16 v[72:75], v[136:139], v[168:171], v[72:75]
	v_mfma_f32_16x16x32_bf16 v[124:127], v[132:135], v[148:151], v[124:127]
	v_mfma_f32_16x16x32_bf16 v[120:123], v[140:143], v[148:151], v[120:123]
	v_mfma_f32_16x16x32_bf16 v[108:111], v[132:135], v[156:159], v[108:111]
	v_mfma_f32_16x16x32_bf16 v[104:107], v[140:143], v[156:159], v[104:107]
	v_mfma_f32_16x16x32_bf16 v[92:95], v[132:135], v[164:167], v[92:95]
	v_mfma_f32_16x16x32_bf16 v[88:91], v[140:143], v[164:167], v[88:91]
	v_mfma_f32_16x16x32_bf16 v[76:79], v[132:135], v[172:175], v[76:79]
	v_mfma_f32_16x16x32_bf16 v[72:75], v[140:143], v[172:175], v[72:75]
	v_mfma_f32_16x16x32_bf16 v[116:119], v[176:179], v[144:147], v[116:119]
	v_mfma_f32_16x16x32_bf16 v[112:115], v[184:187], v[144:147], v[112:115]
	v_mfma_f32_16x16x32_bf16 v[100:103], v[176:179], v[152:155], v[100:103]
	v_mfma_f32_16x16x32_bf16 v[96:99], v[184:187], v[152:155], v[96:99]
	v_mfma_f32_16x16x32_bf16 v[84:87], v[176:179], v[160:163], v[84:87]
	v_mfma_f32_16x16x32_bf16 v[80:83], v[184:187], v[160:163], v[80:83]
	v_mfma_f32_16x16x32_bf16 v[68:71], v[176:179], v[168:171], v[68:71]
	v_mfma_f32_16x16x32_bf16 v[64:67], v[184:187], v[168:171], v[64:67]
	v_mfma_f32_16x16x32_bf16 v[116:119], v[180:183], v[148:151], v[116:119]
	v_mfma_f32_16x16x32_bf16 v[112:115], v[198:201], v[148:151], v[112:115]
	v_mfma_f32_16x16x32_bf16 v[100:103], v[180:183], v[156:159], v[100:103]
	v_mfma_f32_16x16x32_bf16 v[96:99], v[198:201], v[156:159], v[96:99]
	v_mfma_f32_16x16x32_bf16 v[84:87], v[180:183], v[164:167], v[84:87]
	v_mfma_f32_16x16x32_bf16 v[80:83], v[198:201], v[164:167], v[80:83]
	v_mfma_f32_16x16x32_bf16 v[68:71], v[180:183], v[172:175], v[68:71]
	v_mfma_f32_16x16x32_bf16 v[64:67], v[198:201], v[172:175], v[64:67]
	s_barrier
; #define PG8_STAGE(bufoff, gbase, voff) do { _Pragma("unroll") for (int _i = 0; _i < 2; ++_i) \
;         __builtin_amdgcn_global_load_lds((const unsigned*)((const char*)(gbase) + (voff)[_i]), (LAS unsigned*)(lds + (bufoff) + ldsw + _i * 8192), 16, 0, 0); } while (0)
; #define PG8_LDA(dst, b, h) do { _Pragma("unroll") for (int m = 0; m < 4; ++m) _Pragma("unroll") for (int k = 0; k < 2; ++k) dst[m][k] = *(const LAS bf16x8*)(lds + PG8_SA(b, h) + aoff + m * 2048 + k * 1024); } while (0)
; #define PG8_LDB(dst, b, h) do { _Pragma("unroll") for (int n = 0; n < 2; ++n) _Pragma("unroll") for (int k = 0; k < 2; ++k) dst[n][k] = *(const LAS bf16x8*)(lds + PG8_SB(b, h) + boff + n * 2048 + k * 1024); } while (0)
; #define PG8_MMA(ai, bj, At, Bt) do { __builtin_amdgcn_s_setprio(1); _Pragma("unroll") for (int m = 0; m < 4; ++m) _Pragma("unroll") for (int n = 0; n < 2; ++n) _Pragma("unroll") for (int k = 0; k < 2; ++k) \
;         acc[ai][bj][m][n] = __builtin_amdgcn_mfma_f32_16x16x32_bf16(Bt[n][k], At[m][k], acc[ai][bj][m][n], 0, 0, 0); __builtin_amdgcn_s_setprio(0); } while (0)
; #define PG8_WAIT_V(n) asm volatile("s_waitcnt vmcnt(" #n ")" ::: "memory")
; #define PG8_WAIT_L(n) asm volatile("s_waitcnt lgkmcnt(" #n ")" ::: "memory")
; #define PG8_BAR __builtin_amdgcn_s_barrier()
; #define PG8_SCHED __builtin_amdgcn_sched_barrier(0)
; template <class Prog>
; __device__ __forceinline__ void gemm_phase(LAS unsigned char* lds, const int K, const Prog& S) {
;     ...
;             PG8_LDA(At, 0, 1); PG8_STAGE(PG8_SA(0, 0), a2, voffA);
;             PG8_BAR; PG8_WAIT_L(0); PG8_MMA(1, 0, At, B0); PG8_BAR; PG8_SCHED;
;             PG8_STAGE(PG8_SB(0, 1), b2 + hstep, voffB);
;             PG8_WAIT_V(6); PG8_BAR; PG8_MMA(1, 1, At, B1); PG8_BAR;
;             PG8_LDB(B0, 1, 0); PG8_SCHED; PG8_LDA(At, 1, 0); PG8_STAGE(PG8_SA(0, 1), a2 + hstep, voffA);
;             PG8_WAIT_L(8); PG8_BAR; PG8_WAIT_L(0); PG8_MMA(0, 0, At, B0); PG8_BAR; PG8_SCHED;
	ds_read_b128 v[144:147], v217 offset:16384
	ds_read_b128 v[148:151], v217 offset:17408
	ds_read_b128 v[152:155], v217 offset:18432
	ds_read_b128 v[156:159], v217 offset:19456
	s_add_i32 m0, s75, 0x10000
	ds_read_b128 v[160:163], v217 offset:20480
	ds_read_b128 v[164:167], v217 offset:21504
	ds_read_b128 v[168:171], v217 offset:22528
	ds_read_b128 v[172:175], v217 offset:23552
	global_load_lds_dwordx4 v192, s[52:53]
	s_add_i32 m0, s75, 0x12000
	s_nop 0
	global_load_lds_dwordx4 v188, s[52:53]
	s_add_u32 vcc_lo, s52, 0x80000
	s_addc_u32 vcc_hi, s53, 0
	s_add_i32 m0, s75, 0x14000
	s_nop 0
	global_load_lds_dwordx4 v192, vcc
	s_add_i32 m0, s75, 0x16000
	s_nop 0
	global_load_lds_dwordx4 v188, vcc
	s_waitcnt vmcnt(4)
	s_waitcnt lgkmcnt(0)
	s_barrier
	v_mfma_f32_16x16x32_bf16 v[60:63], v[128:131], v[144:147], v[60:63]
	v_mfma_f32_16x16x32_bf16 v[56:59], v[136:139], v[144:147], v[56:59]
	v_mfma_f32_16x16x32_bf16 v[44:47], v[128:131], v[152:155], v[44:47]
	v_mfma_f32_16x16x32_bf16 v[40:43], v[136:139], v[152:155], v[40:43]
	v_mfma_f32_16x16x32_bf16 v[28:31], v[128:131], v[160:163], v[28:31]
	v_mfma_f32_16x16x32_bf16 v[24:27], v[136:139], v[160:163], v[24:27]
	v_mfma_f32_16x16x32_bf16 v[12:15], v[128:131], v[168:171], v[12:15]
	v_mfma_f32_16x16x32_bf16 v[8:11], v[136:139], v[168:171], v[8:11]
	v_mfma_f32_16x16x32_bf16 v[60:63], v[132:135], v[148:151], v[60:63]
	v_mfma_f32_16x16x32_bf16 v[56:59], v[140:143], v[148:151], v[56:59]
	v_mfma_f32_16x16x32_bf16 v[44:47], v[132:135], v[156:159], v[44:47]
	v_mfma_f32_16x16x32_bf16 v[40:43], v[140:143], v[156:159], v[40:43]
	v_mfma_f32_16x16x32_bf16 v[28:31], v[132:135], v[164:167], v[28:31]
	v_mfma_f32_16x16x32_bf16 v[24:27], v[140:143], v[164:167], v[24:27]
	v_mfma_f32_16x16x32_bf16 v[12:15], v[132:135], v[172:175], v[12:15]
	v_mfma_f32_16x16x32_bf16 v[8:11], v[140:143], v[172:175], v[8:11]
	v_mfma_f32_16x16x32_bf16 v[52:55], v[176:179], v[144:147], v[52:55]
	v_mfma_f32_16x16x32_bf16 v[48:51], v[184:187], v[144:147], v[48:51]
	v_mfma_f32_16x16x32_bf16 v[36:39], v[176:179], v[152:155], v[36:39]
	v_mfma_f32_16x16x32_bf16 v[32:35], v[184:187], v[152:155], v[32:35]
	v_mfma_f32_16x16x32_bf16 v[20:23], v[176:179], v[160:163], v[20:23]
	v_mfma_f32_16x16x32_bf16 v[16:19], v[184:187], v[160:163], v[16:19]
	v_mfma_f32_16x16x32_bf16 v[4:7], v[176:179], v[168:171], v[4:7]
	v_mfma_f32_16x16x32_bf16 v[0:3], v[184:187], v[168:171], v[0:3]
	v_mfma_f32_16x16x32_bf16 v[52:55], v[180:183], v[148:151], v[52:55]
	v_mfma_f32_16x16x32_bf16 v[48:51], v[198:201], v[148:151], v[48:51]
	v_mfma_f32_16x16x32_bf16 v[36:39], v[180:183], v[156:159], v[36:39]
	v_mfma_f32_16x16x32_bf16 v[32:35], v[198:201], v[156:159], v[32:35]
	v_mfma_f32_16x16x32_bf16 v[20:23], v[180:183], v[164:167], v[20:23]
	v_mfma_f32_16x16x32_bf16 v[16:19], v[198:201], v[164:167], v[16:19]
	v_mfma_f32_16x16x32_bf16 v[4:7], v[180:183], v[172:175], v[4:7]
	v_mfma_f32_16x16x32_bf16 v[0:3], v[198:201], v[172:175], v[0:3]
	s_barrier
	s_add_u32 vcc_lo, s92, 0x80000
	s_addc_u32 vcc_hi, s93, 0
	ds_read_b128 v[128:131], v202 offset:32768
	ds_read_b128 v[132:135], v202 offset:33792
	ds_read_b128 v[136:139], v202 offset:34816
	ds_read_b128 v[140:143], v202 offset:35840
	s_mov_b32 m0, s75
	ds_read_b128 v[176:179], v202 offset:49152
	ds_read_b128 v[180:183], v202 offset:50176
	ds_read_b128 v[184:187], v202 offset:51200
	ds_read_b128 v[198:201], v202 offset:52224
	global_load_lds_dwordx4 v192, s[92:93]
	s_add_i32 m0, s75, 0x2000
	ds_read_b128 v[144:147], v217 offset:32768
	ds_read_b128 v[148:151], v217 offset:33792
	ds_read_b128 v[152:155], v217 offset:34816
	ds_read_b128 v[156:159], v217 offset:35840
	global_load_lds_dwordx4 v188, s[92:93]
	s_add_i32 m0, s75, 0x4000
	ds_read_b128 v[160:163], v217 offset:36864
	ds_read_b128 v[164:167], v217 offset:37888
	ds_read_b128 v[168:171], v217 offset:38912
	ds_read_b128 v[172:175], v217 offset:39936
	global_load_lds_dwordx4 v192, vcc
	s_add_i32 m0, s75, 0x6000
	s_nop 0
	global_load_lds_dwordx4 v188, vcc
	s_waitcnt lgkmcnt(0)
	s_barrier
	v_mfma_f32_16x16x32_bf16 v[124:127], v[128:131], v[144:147], v[124:127]
	v_mfma_f32_16x16x32_bf16 v[120:123], v[136:139], v[144:147], v[120:123]
	v_mfma_f32_16x16x32_bf16 v[108:111], v[128:131], v[152:155], v[108:111]
	v_mfma_f32_16x16x32_bf16 v[104:107], v[136:139], v[152:155], v[104:107]
	v_mfma_f32_16x16x32_bf16 v[92:95], v[128:131], v[160:163], v[92:95]
	v_mfma_f32_16x16x32_bf16 v[88:91], v[136:139], v[160:163], v[88:91]
	v_mfma_f32_16x16x32_bf16 v[76:79], v[128:131], v[168:171], v[76:79]
	v_mfma_f32_16x16x32_bf16 v[72:75], v[136:139], v[168:171], v[72:75]
	v_mfma_f32_16x16x32_bf16 v[124:127], v[132:135], v[148:151], v[124:127]
	v_mfma_f32_16x16x32_bf16 v[120:123], v[140:143], v[148:151], v[120:123]
	v_mfma_f32_16x16x32_bf16 v[108:111], v[132:135], v[156:159], v[108:111]
	v_mfma_f32_16x16x32_bf16 v[104:107], v[140:143], v[156:159], v[104:107]
	v_mfma_f32_16x16x32_bf16 v[92:95], v[132:135], v[164:167], v[92:95]
	v_mfma_f32_16x16x32_bf16 v[88:91], v[140:143], v[164:167], v[88:91]
	v_mfma_f32_16x16x32_bf16 v[76:79], v[132:135], v[172:175], v[76:79]
	v_mfma_f32_16x16x32_bf16 v[72:75], v[140:143], v[172:175], v[72:75]
	v_mfma_f32_16x16x32_bf16 v[116:119], v[176:179], v[144:147], v[116:119]
	v_mfma_f32_16x16x32_bf16 v[112:115], v[184:187], v[144:147], v[112:115]
	v_mfma_f32_16x16x32_bf16 v[100:103], v[176:179], v[152:155], v[100:103]
	v_mfma_f32_16x16x32_bf16 v[96:99], v[184:187], v[152:155], v[96:99]
	v_mfma_f32_16x16x32_bf16 v[84:87], v[176:179], v[160:163], v[84:87]
	v_mfma_f32_16x16x32_bf16 v[80:83], v[184:187], v[160:163], v[80:83]
	v_mfma_f32_16x16x32_bf16 v[68:71], v[176:179], v[168:171], v[68:71]
	v_mfma_f32_16x16x32_bf16 v[64:67], v[184:187], v[168:171], v[64:67]
	v_mfma_f32_16x16x32_bf16 v[116:119], v[180:183], v[148:151], v[116:119]
	v_mfma_f32_16x16x32_bf16 v[112:115], v[198:201], v[148:151], v[112:115]
	v_mfma_f32_16x16x32_bf16 v[100:103], v[180:183], v[156:159], v[100:103]
	v_mfma_f32_16x16x32_bf16 v[96:99], v[198:201], v[156:159], v[96:99]
	v_mfma_f32_16x16x32_bf16 v[84:87], v[180:183], v[164:167], v[84:87]
	v_mfma_f32_16x16x32_bf16 v[80:83], v[198:201], v[164:167], v[80:83]
	v_mfma_f32_16x16x32_bf16 v[68:71], v[180:183], v[172:175], v[68:71]
	v_mfma_f32_16x16x32_bf16 v[64:67], v[198:201], v[172:175], v[64:67]
	s_barrier
; __device__ __forceinline__ unsigned cvt_pk_bf16(float lo, float hi) { unsigned r; asm volatile("v_cvt_pk_bf16_f32 %0, %1, %2" : "=v"(r) : "v"(lo), "v"(hi)); return r; }
; #define PG8_STAGE(bufoff, gbase, voff) do { _Pragma("unroll") for (int _i = 0; _i < 2; ++_i) \
;         __builtin_amdgcn_global_load_lds((const unsigned*)((const char*)(gbase) + (voff)[_i]), (LAS unsigned*)(lds + (bufoff) + ldsw + _i * 8192), 16, 0, 0); } while (0)
; #define PG8_LDA(dst, b, h) do { _Pragma("unroll") for (int m = 0; m < 4; ++m) _Pragma("unroll") for (int k = 0; k < 2; ++k) dst[m][k] = *(const LAS bf16x8*)(lds + PG8_SA(b, h) + aoff + m * 2048 + k * 1024); } while (0)
; #define PG8_WAIT_V(n) asm volatile("s_waitcnt vmcnt(" #n ")" ::: "memory")
; template <class Prog>
; __device__ __forceinline__ void gemm_phase(LAS unsigned char* lds, const int K, const Prog& S) {
;     ...
;             PG8_LDA(At, 1, 1); PG8_STAGE(PG8_SA(1, 0), a3, voffA);
;             PG8_BAR; PG8_WAIT_L(0); PG8_MMA(1, 0, At, B0); PG8_BAR; PG8_SCHED;
;             PG8_STAGE(PG8_SB(1, 1), b3 + hstep, voffB);
;             PG8_WAIT_V(6); PG8_BAR; PG8_MMA(1, 1, At, B1); PG8_BAR;
;     __device__ __forceinline__ void epi(f32x4 (&acc)[2][2][4][2], const pg8::Unit& u, int wr, int wc, int fr, int fq) const {
;     ...
;         for (int ai = 0; ai < 2; ++ai) {
;             f32x4 xo[4][2][2];
; #pragma unroll
;             for (int m = 0; m < 4; ++m)
; #pragma unroll
;                 for (int bj = 0; bj < 2; ++bj)
; #pragma unroll
;                     for (int n = 0; n < 2; ++n) xo[m][bj][n] = *(const f32x4*)(xin + (size_t)(row0 + ai * 128 + m * 16) * DM + col0 + bj * 128 + n * 16);
; #pragma unroll
;             for (int m = 0; m < 4; ++m) {
;                 const int row = row0 + ai * 128 + m * 16;
;                 const size_t off = (size_t)row * DM + col0;
;                 float ss = 0.f;
; #pragma unroll
;                 for (int bj = 0; bj < 2; ++bj)
; #pragma unroll
;                     for (int n = 0; n < 2; ++n) {
;                         const f32x4 o = xo[m][bj][n] + acc[ai][bj][m][n];
;                         *(f32x4*)(xout + off + bj * 128 + n * 16) = o;
;                         ss += o[0] * o[0] + o[1] * o[1] + o[2] * o[2] + o[3] * o[3];
;                         if (rowss_next) { u32x2 w; w.x = cvt_pk_bf16(o[0], o[1]); w.y = cvt_pk_bf16(o[2], o[3]); *(u32x2*)(xb + off + bj * 128 + n * 16) = w; }
	s_add_u32 vcc_lo, s52, 0x80
	s_addc_u32 vcc_hi, s53, 0
	ds_read_b128 v[144:147], v217 offset:49152
	ds_read_b128 v[148:151], v217 offset:50176
	ds_read_b128 v[152:155], v217 offset:51200
	ds_read_b128 v[156:159], v217 offset:52224
	s_add_i32 m0, s75, 0x18000
	ds_read_b128 v[160:163], v217 offset:53248
	ds_read_b128 v[164:167], v217 offset:54272
	ds_read_b128 v[168:171], v217 offset:55296
	ds_read_b128 v[172:175], v217 offset:56320
	global_load_lds_dwordx4 v192, vcc
	s_add_i32 m0, s75, 0x1a000
	s_nop 0
	global_load_lds_dwordx4 v188, vcc
	s_add_u32 vcc_lo, s52, 0x80080
	s_addc_u32 vcc_hi, s53, 0
	s_add_i32 m0, s75, 0x1c000
	s_nop 0
	global_load_lds_dwordx4 v192, vcc
	s_add_i32 m0, s75, 0x1e000
	s_nop 0
	global_load_lds_dwordx4 v188, vcc
	s_waitcnt vmcnt(4)
	s_waitcnt lgkmcnt(0)
	s_barrier
	v_mfma_f32_16x16x32_bf16 v[60:63], v[128:131], v[144:147], v[60:63]
	v_mfma_f32_16x16x32_bf16 v[56:59], v[136:139], v[144:147], v[56:59]
	v_mfma_f32_16x16x32_bf16 v[44:47], v[128:131], v[152:155], v[44:47]
	v_mfma_f32_16x16x32_bf16 v[40:43], v[136:139], v[152:155], v[40:43]
	v_mfma_f32_16x16x32_bf16 v[28:31], v[128:131], v[160:163], v[28:31]
	v_mfma_f32_16x16x32_bf16 v[24:27], v[136:139], v[160:163], v[24:27]
	v_mfma_f32_16x16x32_bf16 v[12:15], v[128:131], v[168:171], v[12:15]
	v_mfma_f32_16x16x32_bf16 v[8:11], v[136:139], v[168:171], v[8:11]
	v_mfma_f32_16x16x32_bf16 v[60:63], v[132:135], v[148:151], v[60:63]
	v_mfma_f32_16x16x32_bf16 v[56:59], v[140:143], v[148:151], v[56:59]
	v_mfma_f32_16x16x32_bf16 v[44:47], v[132:135], v[156:159], v[44:47]
	v_mfma_f32_16x16x32_bf16 v[40:43], v[140:143], v[156:159], v[40:43]
	v_mfma_f32_16x16x32_bf16 v[28:31], v[132:135], v[164:167], v[28:31]
	v_mfma_f32_16x16x32_bf16 v[24:27], v[140:143], v[164:167], v[24:27]
	v_mfma_f32_16x16x32_bf16 v[12:15], v[132:135], v[172:175], v[12:15]
	v_mfma_f32_16x16x32_bf16 v[8:11], v[140:143], v[172:175], v[8:11]
	v_mfma_f32_16x16x32_bf16 v[52:55], v[176:179], v[144:147], v[52:55]
	v_mfma_f32_16x16x32_bf16 v[48:51], v[184:187], v[144:147], v[48:51]
	v_mfma_f32_16x16x32_bf16 v[36:39], v[176:179], v[152:155], v[36:39]
	v_mfma_f32_16x16x32_bf16 v[32:35], v[184:187], v[152:155], v[32:35]
	v_mfma_f32_16x16x32_bf16 v[20:23], v[176:179], v[160:163], v[20:23]
	v_mfma_f32_16x16x32_bf16 v[16:19], v[184:187], v[160:163], v[16:19]
	v_mfma_f32_16x16x32_bf16 v[4:7], v[176:179], v[168:171], v[4:7]
	v_mfma_f32_16x16x32_bf16 v[0:3], v[184:187], v[168:171], v[0:3]
	v_mfma_f32_16x16x32_bf16 v[52:55], v[180:183], v[148:151], v[52:55]
	v_mfma_f32_16x16x32_bf16 v[48:51], v[198:201], v[148:151], v[48:51]
	v_mfma_f32_16x16x32_bf16 v[36:39], v[180:183], v[156:159], v[36:39]
	v_mfma_f32_16x16x32_bf16 v[32:35], v[198:201], v[156:159], v[32:35]
	v_mfma_f32_16x16x32_bf16 v[20:23], v[180:183], v[164:167], v[20:23]
	v_mfma_f32_16x16x32_bf16 v[16:19], v[198:201], v[164:167], v[16:19]
	v_mfma_f32_16x16x32_bf16 v[4:7], v[180:183], v[172:175], v[4:7]
	v_mfma_f32_16x16x32_bf16 v[0:3], v[198:201], v[172:175], v[0:3]
	s_add_i32 s54, s54, 2
	s_add_u32 s46, s46, 0x100
	s_addc_u32 s47, s47, 0
	s_add_u32 s41, s41, 0x100
	s_addc_u32 s43, s43, 0
	s_cmp_gt_u32 s54, 29
	s_barrier
	s_cbranch_scc0 .LBB0_571
	v_lshl_add_u32 v202, s80, 8, v214
	v_lshl_or_b32 v198, s73, 8, v216
	v_ashrrev_i32_e32 v199, 31, v198
	v_ashrrev_i32_e32 v203, 31, v202
	v_lshl_add_u64 v[200:201], v[198:199], 2, s[8:9]
	v_lshlrev_b64 v[128:129], 13, v[202:203]
	v_or_b32_e32 v208, 16, v202
	v_lshl_add_u64 v[128:129], v[200:201], 0, v[128:129]
	v_ashrrev_i32_e32 v209, 31, v208
	global_load_dwordx4 v[210:213], v[128:129], off
	global_load_dwordx4 v[184:187], v[128:129], off offset:64
	global_load_dwordx4 v[180:183], v[128:129], off offset:512
	global_load_dwordx4 v[176:179], v[128:129], off offset:576
	v_lshlrev_b64 v[128:129], 13, v[208:209]
	v_or_b32_e32 v206, 32, v202
	v_lshl_add_u64 v[128:129], v[200:201], 0, v[128:129]
	v_ashrrev_i32_e32 v207, 31, v206
	global_load_dwordx4 v[172:175], v[128:129], off
	global_load_dwordx4 v[168:171], v[128:129], off offset:64
	global_load_dwordx4 v[164:167], v[128:129], off offset:512
	global_load_dwordx4 v[160:163], v[128:129], off offset:576
	v_lshlrev_b64 v[128:129], 13, v[206:207]
	v_or_b32_e32 v204, 48, v202
	v_lshl_add_u64 v[128:129], v[200:201], 0, v[128:129]
	v_ashrrev_i32_e32 v205, 31, v204
	global_load_dwordx4 v[156:159], v[128:129], off
	global_load_dwordx4 v[152:155], v[128:129], off offset:64
	global_load_dwordx4 v[148:151], v[128:129], off offset:512
	global_load_dwordx4 v[144:147], v[128:129], off offset:576
	v_lshlrev_b64 v[128:129], 13, v[204:205]
	v_lshl_add_u64 v[128:129], v[200:201], 0, v[128:129]
	global_load_dwordx4 v[140:143], v[128:129], off
	global_load_dwordx4 v[136:139], v[128:129], off offset:64
	global_load_dwordx4 v[132:135], v[128:129], off offset:512
	s_nop 0
	global_load_dwordx4 v[128:131], v[128:129], off offset:576
	v_lshlrev_b64 v[218:219], 11, v[202:203]
	v_lshl_add_u64 v[218:219], v[218:219], 0, v[198:199]
	s_andn2_b64 vcc, exec, s[12:13]
	s_waitcnt vmcnt(0)
	v_pk_add_f32 v[126:127], v[126:127], v[212:213]
	v_cndmask_b32_e64 v212, 0, 1, s[12:13]
	v_pk_add_f32 v[124:125], v[124:125], v[210:211]
	v_lshl_add_u64 v[210:211], v[218:219], 2, s[48:49]
	v_cmp_ne_u32_e64 s[6:7], 1, v212
	v_lshl_add_u64 v[212:213], v[218:219], 1, s[20:21]
	global_store_dwordx4 v[210:211], v[124:127], off
	s_cbranch_vccnz .LBB0_574
	v_cvt_pk_bf16_f32 v218, v124, v125
	v_cvt_pk_bf16_f32 v219, v126, v127
	global_store_dwordx2 v[212:213], v[218:219], off
